# v26: v15 + all six GEMM K-loops with LDS-DMA loads in scalar-base form (no address VALU in load phases), flag compare through SALU
# speedup vs baseline: 1.0052x; 1.0040x over previous
.LBB0_687:
	s_cmp_eq_u32 s12, 2
	s_cselect_b32 s4, 0x4c0000, 0
	s_cmp_eq_u32 s69, 2
	s_cselect_b64 s[58:59], -1, 0
	s_ashr_i32 s45, s44, 31
	s_lshl_b64 s[6:7], s[44:45], 20
	s_add_u32 s48, s72, s6
	s_addc_u32 s49, s73, s7
	s_and_b64 s[6:7], s[56:57], exec
	s_cselect_b32 s34, s49, s43
	s_cselect_b32 s35, s48, s42
	s_add_u32 s6, s54, 0x80
	s_addc_u32 s7, s55, 0
	v_lshl_add_u64 v[0:1], s[6:7], 0, v[206:207]
	v_lshl_add_u64 v[210:211], v[0:1], 0, s[52:53]
	v_lshl_add_u64 v[0:1], s[6:7], 0, v[208:209]
	v_mov_b32_e32 v97, v96
	v_lshl_add_u64 v[212:213], v[0:1], 0, s[52:53]
	s_add_u32 s45, s42, 0x100
	v_mov_b32_e32 v98, v96
	v_mov_b32_e32 v99, v96
	v_mov_b32_e32 v64, 0
	v_mov_b64_e32 v[0:1], v[96:97]
	v_mov_b64_e32 v[4:5], v[96:97]
	v_mov_b64_e32 v[16:17], v[96:97]
	v_mov_b64_e32 v[20:21], v[96:97]
	v_mov_b64_e32 v[32:33], v[96:97]
	v_mov_b64_e32 v[36:37], v[96:97]
	v_mov_b64_e32 v[48:49], v[96:97]
	v_mov_b64_e32 v[52:53], v[96:97]
	v_mov_b64_e32 v[8:9], v[96:97]
	v_mov_b64_e32 v[12:13], v[96:97]
	v_mov_b64_e32 v[24:25], v[96:97]
	v_mov_b64_e32 v[28:29], v[96:97]
	v_mov_b64_e32 v[40:41], v[96:97]
	v_mov_b64_e32 v[44:45], v[96:97]
	v_mov_b64_e32 v[56:57], v[96:97]
	v_mov_b64_e32 v[60:61], v[96:97]
	s_addc_u32 s10, s43, 0
	s_mov_b32 s6, -2
	s_mov_b64 s[60:61], 0
	v_mov_b64_e32 v[2:3], v[98:99]
	v_mov_b64_e32 v[6:7], v[98:99]
	v_mov_b64_e32 v[18:19], v[98:99]
	v_mov_b64_e32 v[22:23], v[98:99]
	v_mov_b64_e32 v[34:35], v[98:99]
	v_mov_b64_e32 v[38:39], v[98:99]
	v_mov_b64_e32 v[50:51], v[98:99]
	v_mov_b64_e32 v[54:55], v[98:99]
	v_mov_b64_e32 v[10:11], v[98:99]
	v_mov_b64_e32 v[14:15], v[98:99]
	v_mov_b64_e32 v[26:27], v[98:99]
	v_mov_b64_e32 v[30:31], v[98:99]
	v_mov_b64_e32 v[42:43], v[98:99]
	v_mov_b64_e32 v[46:47], v[98:99]
	v_mov_b64_e32 v[58:59], v[98:99]
	v_mov_b64_e32 v[62:63], v[98:99]
	v_mov_b32_e32 v65, v64
	v_mov_b32_e32 v66, v64
	v_mov_b32_e32 v67, v64
	v_mov_b32_e32 v68, v64
	v_mov_b32_e32 v69, v64
	v_mov_b32_e32 v70, v64
	v_mov_b32_e32 v71, v64
	v_mov_b32_e32 v80, v64
	v_mov_b32_e32 v81, v64
	v_mov_b32_e32 v82, v64
	v_mov_b32_e32 v83, v64
	v_mov_b32_e32 v84, v64
	v_mov_b32_e32 v85, v64
	v_mov_b32_e32 v86, v64
	v_mov_b32_e32 v87, v64
	v_mov_b32_e32 v98, v64
	v_mov_b32_e32 v99, v64
	v_mov_b32_e32 v100, v64
	v_mov_b32_e32 v101, v64
	v_mov_b32_e32 v106, v64
	v_mov_b32_e32 v107, v64
	v_mov_b32_e32 v108, v64
	v_mov_b32_e32 v109, v64
	v_mov_b32_e32 v126, v64
	v_mov_b32_e32 v127, v64
	v_mov_b32_e32 v128, v64
	v_mov_b32_e32 v129, v64
	v_mov_b32_e32 v130, v64
	v_mov_b32_e32 v131, v64
	v_mov_b32_e32 v132, v64
	v_mov_b32_e32 v133, v64
	v_mov_b32_e32 v72, v64
	v_mov_b32_e32 v73, v64
	v_mov_b32_e32 v74, v64
	v_mov_b32_e32 v75, v64
	v_mov_b32_e32 v76, v64
	v_mov_b32_e32 v77, v64
	v_mov_b32_e32 v78, v64
	v_mov_b32_e32 v79, v64
	v_mov_b32_e32 v88, v64
	v_mov_b32_e32 v89, v64
	v_mov_b32_e32 v90, v64
	v_mov_b32_e32 v91, v64
	v_mov_b32_e32 v92, v64
	v_mov_b32_e32 v93, v64
	v_mov_b32_e32 v94, v64
	v_mov_b32_e32 v95, v64
	v_mov_b32_e32 v114, v64
	v_mov_b32_e32 v115, v64
	v_mov_b32_e32 v116, v64
	v_mov_b32_e32 v117, v64
	v_mov_b32_e32 v118, v64
	v_mov_b32_e32 v119, v64
	v_mov_b32_e32 v120, v64
	v_mov_b32_e32 v121, v64
	v_mov_b32_e32 v150, v64
	v_mov_b32_e32 v151, v64
	v_mov_b32_e32 v152, v64
	v_mov_b32_e32 v153, v64
	v_mov_b32_e32 v154, v64
	v_mov_b32_e32 v155, v64
	v_mov_b32_e32 v156, v64
	v_mov_b32_e32 v157, v64
	v_add_u32_e32 v250, 0x10000, v222
	v_add_u32_e32 v251, 0x14000, v222
	v_add_u32_e32 v252, 0x18000, v222
	v_add_u32_e32 v253, 0x1c000, v222
	s_branch .LBB0_689

.LBB0_689:
	s_add_u32 s7, s54, s60
	s_addc_u32 s11, s55, s61
	s_add_u32 s7, s7, 0x100
	s_addc_u32 s11, s11, 0
	s_add_i32 s42, 0, 0x10000
	s_add_u32 s43, s45, s60
	s_addc_u32 s62, s10, s61
	s_cmpk_eq_i32 s60, 0xf00
	s_cselect_b64 s[66:67], -1, 0
	s_and_b64 s[26:27], s[66:67], exec
	s_cselect_b32 s65, s47, s11
	s_cselect_b32 s64, s46, s7
	s_cselect_b32 s63, s34, s62
	s_cselect_b32 s62, s35, s43
	s_add_i32 s7, 0, 0x14000
	ds_read_b128 v[158:161], v250
	ds_read_b128 v[162:165], v250 offset:1024
	ds_read_b128 v[166:169], v250 offset:2048
	ds_read_b128 v[170:173], v250 offset:3072
	ds_read_b128 v[134:137], v251
	ds_read_b128 v[138:141], v251 offset:1024
	ds_read_b128 v[142:145], v251 offset:2048
	ds_read_b128 v[146:149], v251 offset:3072
	s_waitcnt lgkmcnt(0)
	v_lshl_add_u64 v[102:103], v[212:213], 0, s[60:61]
	s_add_i32 m0, s51, 0xc000
	ds_read_b128 v[174:177], v224
	ds_read_b128 v[178:181], v224 offset:1024
	ds_read_b128 v[182:185], v224 offset:2048
	ds_read_b128 v[186:189], v224 offset:3072
	ds_read_b128 v[190:193], v224 offset:4096
	ds_read_b128 v[214:217], v224 offset:5120
	ds_read_b128 v[218:221], v224 offset:6144
	ds_read_b128 v[226:229], v224 offset:7168
	global_load_lds_dwordx4 v[102:103], off
	v_lshl_add_u64 v[102:103], v[210:211], 0, s[60:61]
	s_add_i32 m0, s51, 0xe000
	s_nop 0
	global_load_lds_dwordx4 v[102:103], off
	s_waitcnt vmcnt(8)
	s_waitcnt lgkmcnt(0)
	s_barrier
	s_setprio 1
	s_waitcnt lgkmcnt(0)
	v_mfma_f32_16x16x32_bf16 v[102:105], v[158:161], v[174:177], v[154:157]
	v_mfma_f32_16x16x32_bf16 v[110:113], v[166:169], v[174:177], v[150:153]
	v_mfma_f32_16x16x32_bf16 v[118:121], v[158:161], v[182:185], v[118:121]
	v_mfma_f32_16x16x32_bf16 v[114:117], v[166:169], v[182:185], v[114:117]
	v_mfma_f32_16x16x32_bf16 v[92:95], v[158:161], v[190:193], v[92:95]
	v_mfma_f32_16x16x32_bf16 v[88:91], v[166:169], v[190:193], v[88:91]
	v_mfma_f32_16x16x32_bf16 v[76:79], v[158:161], v[218:221], v[76:79]
	v_mfma_f32_16x16x32_bf16 v[72:75], v[166:169], v[218:221], v[72:75]
	v_mfma_f32_16x16x32_bf16 v[102:105], v[162:165], v[178:181], v[102:105]
	v_mfma_f32_16x16x32_bf16 v[110:113], v[170:173], v[178:181], v[110:113]
	v_mfma_f32_16x16x32_bf16 v[118:121], v[162:165], v[186:189], v[118:121]
	v_mfma_f32_16x16x32_bf16 v[114:117], v[170:173], v[186:189], v[114:117]
	v_mfma_f32_16x16x32_bf16 v[92:95], v[162:165], v[214:217], v[92:95]
	v_mfma_f32_16x16x32_bf16 v[88:91], v[170:173], v[214:217], v[88:91]
	v_mfma_f32_16x16x32_bf16 v[76:79], v[162:165], v[226:229], v[76:79]
	v_mfma_f32_16x16x32_bf16 v[72:75], v[170:173], v[226:229], v[72:75]
	s_setprio 0
	s_setprio 1
	v_mfma_f32_16x16x32_bf16 v[122:125], v[134:137], v[174:177], v[130:133]
	v_mfma_f32_16x16x32_bf16 v[126:129], v[142:145], v[174:177], v[126:129]
	v_mfma_f32_16x16x32_bf16 v[106:109], v[134:137], v[182:185], v[106:109]
	v_mfma_f32_16x16x32_bf16 v[98:101], v[142:145], v[182:185], v[98:101]
	v_mfma_f32_16x16x32_bf16 v[84:87], v[134:137], v[190:193], v[84:87]
	v_mfma_f32_16x16x32_bf16 v[80:83], v[142:145], v[190:193], v[80:83]
	v_mfma_f32_16x16x32_bf16 v[68:71], v[134:137], v[218:221], v[68:71]
	v_mfma_f32_16x16x32_bf16 v[64:67], v[142:145], v[218:221], v[64:67]
	v_mfma_f32_16x16x32_bf16 v[122:125], v[138:141], v[178:181], v[122:125]
	v_mfma_f32_16x16x32_bf16 v[126:129], v[146:149], v[178:181], v[126:129]
	v_mfma_f32_16x16x32_bf16 v[106:109], v[138:141], v[186:189], v[106:109]
	v_mfma_f32_16x16x32_bf16 v[98:101], v[146:149], v[186:189], v[98:101]
	v_mfma_f32_16x16x32_bf16 v[84:87], v[138:141], v[214:217], v[84:87]
	v_mfma_f32_16x16x32_bf16 v[80:83], v[146:149], v[214:217], v[80:83]
	v_mfma_f32_16x16x32_bf16 v[68:71], v[138:141], v[226:229], v[68:71]
	v_mfma_f32_16x16x32_bf16 v[64:67], v[146:149], v[226:229], v[64:67]
	s_setprio 0
	s_barrier
	s_add_i32 s11, s42, s74
	s_mov_b32 m0, s11
	ds_read_b128 v[186:189], v224 offset:16384
	ds_read_b128 v[190:193], v224 offset:17408
	ds_read_b128 v[178:181], v224 offset:18432
	ds_read_b128 v[182:185], v224 offset:19456
	ds_read_b128 v[154:157], v224 offset:20480
	ds_read_b128 v[174:177], v224 offset:21504
	ds_read_b128 v[130:133], v224 offset:22528
	ds_read_b128 v[150:153], v224 offset:23552
	global_load_lds_dwordx4 v200, s[62:63]
	s_add_i32 m0, s11, 0x2000
	s_add_u32 s26, s62, 0x80000
	s_addc_u32 s27, s63, 0
	s_add_i32 s7, s7, s74
	global_load_lds_dwordx4 v204, s[62:63]
	s_mov_b32 m0, s7
	s_nop 0
	global_load_lds_dwordx4 v200, s[26:27]
	s_add_i32 m0, s7, 0x2000
	s_nop 0
	global_load_lds_dwordx4 v204, s[26:27]
	s_mov_b32 m0, s51
	s_andn2_b64 s[42:43], exec, s[58:59]
	global_load_lds_dwordx4 v198, s[64:65]
	s_mov_b32 m0, s75
	s_andn2_b64 vcc, exec, s[58:59]
	global_load_lds_dwordx4 v202, s[64:65]
	s_waitcnt vmcnt(8)
	s_waitcnt lgkmcnt(0)
	s_barrier
	s_cbranch_vccnz .LBB0_691
	s_setprio 1
	s_waitcnt lgkmcnt(0)
	v_mfma_f32_16x16x32_bf16 v[60:63], v[158:161], v[186:189], v[60:63]
	v_mfma_f32_16x16x32_bf16 v[56:59], v[166:169], v[186:189], v[56:59]
	v_mfma_f32_16x16x32_bf16 v[44:47], v[158:161], v[178:181], v[44:47]
	v_mfma_f32_16x16x32_bf16 v[40:43], v[166:169], v[178:181], v[40:43]
	v_mfma_f32_16x16x32_bf16 v[28:31], v[158:161], v[154:157], v[28:31]
	v_mfma_f32_16x16x32_bf16 v[24:27], v[166:169], v[154:157], v[24:27]
	v_mfma_f32_16x16x32_bf16 v[12:15], v[158:161], v[130:133], v[12:15]
	v_mfma_f32_16x16x32_bf16 v[8:11], v[166:169], v[130:133], v[8:11]
	v_mfma_f32_16x16x32_bf16 v[60:63], v[162:165], v[190:193], v[60:63]
	v_mfma_f32_16x16x32_bf16 v[56:59], v[170:173], v[190:193], v[56:59]
	v_mfma_f32_16x16x32_bf16 v[44:47], v[162:165], v[182:185], v[44:47]
	v_mfma_f32_16x16x32_bf16 v[40:43], v[170:173], v[182:185], v[40:43]
	v_mfma_f32_16x16x32_bf16 v[28:31], v[162:165], v[174:177], v[28:31]
	v_mfma_f32_16x16x32_bf16 v[24:27], v[170:173], v[174:177], v[24:27]
	v_mfma_f32_16x16x32_bf16 v[12:15], v[162:165], v[150:153], v[12:15]
	v_mfma_f32_16x16x32_bf16 v[8:11], v[170:173], v[150:153], v[8:11]
	s_setprio 0
	s_setprio 1
	v_mfma_f32_16x16x32_bf16 v[52:55], v[134:137], v[186:189], v[52:55]
	v_mfma_f32_16x16x32_bf16 v[48:51], v[142:145], v[186:189], v[48:51]
	v_mfma_f32_16x16x32_bf16 v[36:39], v[134:137], v[178:181], v[36:39]
	v_mfma_f32_16x16x32_bf16 v[32:35], v[142:145], v[178:181], v[32:35]
	v_mfma_f32_16x16x32_bf16 v[20:23], v[134:137], v[154:157], v[20:23]
	v_mfma_f32_16x16x32_bf16 v[16:19], v[142:145], v[154:157], v[16:19]
	v_mfma_f32_16x16x32_bf16 v[4:7], v[134:137], v[130:133], v[4:7]
	v_mfma_f32_16x16x32_bf16 v[0:3], v[142:145], v[130:133], v[0:3]
	v_mfma_f32_16x16x32_bf16 v[52:55], v[138:141], v[190:193], v[52:55]
	v_mfma_f32_16x16x32_bf16 v[48:51], v[146:149], v[190:193], v[48:51]
	v_mfma_f32_16x16x32_bf16 v[36:39], v[138:141], v[182:185], v[36:39]
	v_mfma_f32_16x16x32_bf16 v[32:35], v[146:149], v[182:185], v[32:35]
	v_mfma_f32_16x16x32_bf16 v[20:23], v[138:141], v[174:177], v[20:23]
	v_mfma_f32_16x16x32_bf16 v[16:19], v[146:149], v[174:177], v[16:19]
	v_mfma_f32_16x16x32_bf16 v[4:7], v[138:141], v[150:153], v[4:7]
	v_mfma_f32_16x16x32_bf16 v[0:3], v[146:149], v[150:153], v[0:3]
	s_setprio 0
.LBB0_691:
	s_and_b64 s[26:27], s[56:57], s[66:67]
	s_and_b64 s[26:27], s[26:27], exec
	s_cselect_b32 s7, 0, s53
	s_cselect_b32 s11, s4, s52
	s_barrier
	s_add_i32 s66, 0, 0x18000
	s_add_i32 s67, 0, 0x1c000
	ds_read_b128 v[158:161], v252
	ds_read_b128 v[162:165], v252 offset:1024
	ds_read_b128 v[166:169], v252 offset:2048
	ds_read_b128 v[170:173], v252 offset:3072
	ds_read_b128 v[134:137], v253
	ds_read_b128 v[138:141], v253 offset:1024
	ds_read_b128 v[142:145], v253 offset:2048
	ds_read_b128 v[146:149], v253 offset:3072
	s_add_u32 s26, s64, s11
	s_addc_u32 s27, s65, s7
	s_mov_b32 m0, s76
	s_waitcnt lgkmcnt(0)
	ds_read_b128 v[174:177], v224 offset:32768
	ds_read_b128 v[178:181], v224 offset:33792
	ds_read_b128 v[182:185], v224 offset:34816
	ds_read_b128 v[186:189], v224 offset:35840
	ds_read_b128 v[190:193], v224 offset:36864
	ds_read_b128 v[226:229], v224 offset:37888
	ds_read_b128 v[230:233], v224 offset:38912
	ds_read_b128 v[234:237], v224 offset:39936
	global_load_lds_dwordx4 v198, s[26:27]
	s_mov_b32 m0, s77
	s_nop 0
	global_load_lds_dwordx4 v202, s[26:27]
	s_waitcnt vmcnt(8)
	s_waitcnt lgkmcnt(0)
	s_barrier
	s_setprio 1
	s_waitcnt lgkmcnt(0)
	v_mfma_f32_16x16x32_bf16 v[102:105], v[158:161], v[174:177], v[102:105]
	v_mfma_f32_16x16x32_bf16 v[154:157], v[162:165], v[178:181], v[102:105]
	v_mfma_f32_16x16x32_bf16 v[102:105], v[166:169], v[174:177], v[110:113]
	v_mfma_f32_16x16x32_bf16 v[150:153], v[170:173], v[178:181], v[102:105]
	v_mfma_f32_16x16x32_bf16 v[102:105], v[158:161], v[182:185], v[118:121]
	v_mfma_f32_16x16x32_bf16 v[118:121], v[162:165], v[186:189], v[102:105]
	v_mfma_f32_16x16x32_bf16 v[102:105], v[166:169], v[182:185], v[114:117]
	v_mfma_f32_16x16x32_bf16 v[92:95], v[158:161], v[190:193], v[92:95]
	v_mfma_f32_16x16x32_bf16 v[88:91], v[166:169], v[190:193], v[88:91]
	v_mfma_f32_16x16x32_bf16 v[76:79], v[158:161], v[230:233], v[76:79]
	v_mfma_f32_16x16x32_bf16 v[72:75], v[166:169], v[230:233], v[72:75]
	v_mfma_f32_16x16x32_bf16 v[114:117], v[170:173], v[186:189], v[102:105]
	v_mfma_f32_16x16x32_bf16 v[92:95], v[162:165], v[226:229], v[92:95]
	v_mfma_f32_16x16x32_bf16 v[88:91], v[170:173], v[226:229], v[88:91]
	v_mfma_f32_16x16x32_bf16 v[76:79], v[162:165], v[234:237], v[76:79]
	v_mfma_f32_16x16x32_bf16 v[72:75], v[170:173], v[234:237], v[72:75]
	s_setprio 0
	s_setprio 1
	v_mfma_f32_16x16x32_bf16 v[102:105], v[134:137], v[174:177], v[122:125]
	v_mfma_f32_16x16x32_bf16 v[130:133], v[138:141], v[178:181], v[102:105]
	v_mfma_f32_16x16x32_bf16 v[102:105], v[142:145], v[174:177], v[126:129]
	v_mfma_f32_16x16x32_bf16 v[126:129], v[146:149], v[178:181], v[102:105]
	v_mfma_f32_16x16x32_bf16 v[102:105], v[134:137], v[182:185], v[106:109]
	v_mfma_f32_16x16x32_bf16 v[98:101], v[142:145], v[182:185], v[98:101]
	v_mfma_f32_16x16x32_bf16 v[84:87], v[134:137], v[190:193], v[84:87]
	v_mfma_f32_16x16x32_bf16 v[80:83], v[142:145], v[190:193], v[80:83]
	v_mfma_f32_16x16x32_bf16 v[68:71], v[134:137], v[230:233], v[68:71]
	v_mfma_f32_16x16x32_bf16 v[64:67], v[142:145], v[230:233], v[64:67]
	v_mfma_f32_16x16x32_bf16 v[106:109], v[138:141], v[186:189], v[102:105]
	v_mfma_f32_16x16x32_bf16 v[98:101], v[146:149], v[186:189], v[98:101]
	v_mfma_f32_16x16x32_bf16 v[84:87], v[138:141], v[226:229], v[84:87]
	v_mfma_f32_16x16x32_bf16 v[80:83], v[146:149], v[226:229], v[80:83]
	v_mfma_f32_16x16x32_bf16 v[68:71], v[138:141], v[234:237], v[68:71]
	v_mfma_f32_16x16x32_bf16 v[64:67], v[146:149], v[234:237], v[64:67]
	s_setprio 0
	s_barrier
	s_add_i32 s7, s66, s74
	s_add_i32 m0, s7, 0xffffff80
	ds_read_b128 v[186:189], v224 offset:49152
	ds_read_b128 v[190:193], v224 offset:50176
	ds_read_b128 v[178:181], v224 offset:51200
	ds_read_b128 v[182:185], v224 offset:52224
	ds_read_b128 v[122:125], v224 offset:53248
	ds_read_b128 v[174:177], v224 offset:54272
	ds_read_b128 v[102:105], v224 offset:55296
	ds_read_b128 v[110:113], v224 offset:56320
	global_load_lds_dwordx4 v200, s[62:63] offset:128
	s_add_i32 m0, s7, 0x1f80
	s_add_u32 s26, s62, 0x80080
	s_addc_u32 s27, s63, 0
	s_add_i32 s7, s67, s74
	global_load_lds_dwordx4 v204, s[62:63] offset:128
	s_mov_b32 m0, s7
	s_and_b64 vcc, exec, s[42:43]
	global_load_lds_dwordx4 v200, s[26:27]
	s_add_i32 m0, s7, 0x2000
	s_nop 0
	global_load_lds_dwordx4 v204, s[26:27]
	s_add_i32 m0, s78, 0xffffff80
	s_nop 0
	global_load_lds_dwordx4 v198, s[64:65] offset:128
	s_add_i32 m0, s79, 0xffffff80
	s_nop 0
	global_load_lds_dwordx4 v202, s[64:65] offset:128
	s_waitcnt vmcnt(8)
	s_waitcnt lgkmcnt(0)
	s_barrier
	s_cbranch_vccnz .LBB0_688
	s_setprio 1
	s_waitcnt lgkmcnt(0)
	v_mfma_f32_16x16x32_bf16 v[60:63], v[158:161], v[186:189], v[60:63]
	v_mfma_f32_16x16x32_bf16 v[56:59], v[166:169], v[186:189], v[56:59]
	v_mfma_f32_16x16x32_bf16 v[44:47], v[158:161], v[178:181], v[44:47]
	v_mfma_f32_16x16x32_bf16 v[40:43], v[166:169], v[178:181], v[40:43]
	v_mfma_f32_16x16x32_bf16 v[28:31], v[158:161], v[122:125], v[28:31]
	v_mfma_f32_16x16x32_bf16 v[24:27], v[166:169], v[122:125], v[24:27]
	v_mfma_f32_16x16x32_bf16 v[12:15], v[158:161], v[102:105], v[12:15]
	v_mfma_f32_16x16x32_bf16 v[8:11], v[166:169], v[102:105], v[8:11]
	v_mfma_f32_16x16x32_bf16 v[60:63], v[162:165], v[190:193], v[60:63]
	v_mfma_f32_16x16x32_bf16 v[56:59], v[170:173], v[190:193], v[56:59]
	v_mfma_f32_16x16x32_bf16 v[44:47], v[162:165], v[182:185], v[44:47]
	v_mfma_f32_16x16x32_bf16 v[40:43], v[170:173], v[182:185], v[40:43]
	v_mfma_f32_16x16x32_bf16 v[28:31], v[162:165], v[174:177], v[28:31]
	v_mfma_f32_16x16x32_bf16 v[24:27], v[170:173], v[174:177], v[24:27]
	v_mfma_f32_16x16x32_bf16 v[12:15], v[162:165], v[110:113], v[12:15]
	v_mfma_f32_16x16x32_bf16 v[8:11], v[170:173], v[110:113], v[8:11]
	s_setprio 0
	s_setprio 1
	v_mfma_f32_16x16x32_bf16 v[52:55], v[134:137], v[186:189], v[52:55]
	v_mfma_f32_16x16x32_bf16 v[48:51], v[142:145], v[186:189], v[48:51]
	v_mfma_f32_16x16x32_bf16 v[36:39], v[134:137], v[178:181], v[36:39]
	v_mfma_f32_16x16x32_bf16 v[32:35], v[142:145], v[178:181], v[32:35]
	v_mfma_f32_16x16x32_bf16 v[20:23], v[134:137], v[122:125], v[20:23]
	v_mfma_f32_16x16x32_bf16 v[16:19], v[142:145], v[122:125], v[16:19]
	v_mfma_f32_16x16x32_bf16 v[4:7], v[134:137], v[102:105], v[4:7]
	v_mfma_f32_16x16x32_bf16 v[0:3], v[142:145], v[102:105], v[0:3]
	v_mfma_f32_16x16x32_bf16 v[52:55], v[138:141], v[190:193], v[52:55]
	v_mfma_f32_16x16x32_bf16 v[48:51], v[146:149], v[190:193], v[48:51]
	v_mfma_f32_16x16x32_bf16 v[36:39], v[138:141], v[182:185], v[36:39]
	v_mfma_f32_16x16x32_bf16 v[32:35], v[146:149], v[182:185], v[32:35]
	v_mfma_f32_16x16x32_bf16 v[20:23], v[138:141], v[174:177], v[20:23]
	v_mfma_f32_16x16x32_bf16 v[16:19], v[146:149], v[174:177], v[16:19]
	v_mfma_f32_16x16x32_bf16 v[4:7], v[138:141], v[110:113], v[4:7]
	v_mfma_f32_16x16x32_bf16 v[0:3], v[146:149], v[110:113], v[0:3]
	s_setprio 0
	s_branch .LBB0_688

.LBB0_727:
	s_cmp_eq_u32 s77, 2
	s_cselect_b32 s4, 0x4c0000, 0
	s_cmp_eq_u32 s78, 2
	s_cselect_b64 s[58:59], -1, 0
	s_ashr_i32 s45, s44, 31
	s_lshl_b64 s[6:7], s[44:45], 20
	s_add_u32 s48, s34, s6
	s_addc_u32 s49, s35, s7
	s_and_b64 s[6:7], s[56:57], exec
	s_cselect_b32 s45, s49, s43
	s_cselect_b32 s80, s48, s42
	s_add_u32 s6, s54, 0x80
	s_addc_u32 s7, s55, 0
	v_lshl_add_u64 v[0:1], s[6:7], 0, v[206:207]
	v_lshl_add_u64 v[210:211], v[0:1], 0, s[52:53]
	v_lshl_add_u64 v[0:1], s[6:7], 0, v[208:209]
	v_mov_b32_e32 v97, v96
	v_lshl_add_u64 v[212:213], v[0:1], 0, s[52:53]
	s_add_u32 s81, s42, 0x100
	v_mov_b32_e32 v98, v96
	v_mov_b32_e32 v99, v96
	v_mov_b32_e32 v64, 0
	v_mov_b64_e32 v[0:1], v[96:97]
	v_mov_b64_e32 v[4:5], v[96:97]
	v_mov_b64_e32 v[16:17], v[96:97]
	v_mov_b64_e32 v[20:21], v[96:97]
	v_mov_b64_e32 v[32:33], v[96:97]
	v_mov_b64_e32 v[36:37], v[96:97]
	v_mov_b64_e32 v[48:49], v[96:97]
	v_mov_b64_e32 v[52:53], v[96:97]
	v_mov_b64_e32 v[8:9], v[96:97]
	v_mov_b64_e32 v[12:13], v[96:97]
	v_mov_b64_e32 v[24:25], v[96:97]
	v_mov_b64_e32 v[28:29], v[96:97]
	v_mov_b64_e32 v[40:41], v[96:97]
	v_mov_b64_e32 v[44:45], v[96:97]
	v_mov_b64_e32 v[56:57], v[96:97]
	v_mov_b64_e32 v[60:61], v[96:97]
	s_addc_u32 s10, s43, 0
	s_mov_b32 s6, -2
	s_mov_b64 s[60:61], 0
	v_mov_b64_e32 v[2:3], v[98:99]
	v_mov_b64_e32 v[6:7], v[98:99]
	v_mov_b64_e32 v[18:19], v[98:99]
	v_mov_b64_e32 v[22:23], v[98:99]
	v_mov_b64_e32 v[34:35], v[98:99]
	v_mov_b64_e32 v[38:39], v[98:99]
	v_mov_b64_e32 v[50:51], v[98:99]
	v_mov_b64_e32 v[54:55], v[98:99]
	v_mov_b64_e32 v[10:11], v[98:99]
	v_mov_b64_e32 v[14:15], v[98:99]
	v_mov_b64_e32 v[26:27], v[98:99]
	v_mov_b64_e32 v[30:31], v[98:99]
	v_mov_b64_e32 v[42:43], v[98:99]
	v_mov_b64_e32 v[46:47], v[98:99]
	v_mov_b64_e32 v[58:59], v[98:99]
	v_mov_b64_e32 v[62:63], v[98:99]
	v_mov_b32_e32 v65, v64
	v_mov_b32_e32 v66, v64
	v_mov_b32_e32 v67, v64
	v_mov_b32_e32 v68, v64
	v_mov_b32_e32 v69, v64
	v_mov_b32_e32 v70, v64
	v_mov_b32_e32 v71, v64
	v_mov_b32_e32 v80, v64
	v_mov_b32_e32 v81, v64
	v_mov_b32_e32 v82, v64
	v_mov_b32_e32 v83, v64
	v_mov_b32_e32 v84, v64
	v_mov_b32_e32 v85, v64
	v_mov_b32_e32 v86, v64
	v_mov_b32_e32 v87, v64
	v_mov_b32_e32 v98, v64
	v_mov_b32_e32 v99, v64
	v_mov_b32_e32 v100, v64
	v_mov_b32_e32 v101, v64
	v_mov_b32_e32 v102, v64
	v_mov_b32_e32 v103, v64
	v_mov_b32_e32 v104, v64
	v_mov_b32_e32 v105, v64
	v_mov_b32_e32 v114, v64
	v_mov_b32_e32 v115, v64
	v_mov_b32_e32 v116, v64
	v_mov_b32_e32 v117, v64
	v_mov_b32_e32 v118, v64
	v_mov_b32_e32 v119, v64
	v_mov_b32_e32 v120, v64
	v_mov_b32_e32 v121, v64
	v_mov_b32_e32 v72, v64
	v_mov_b32_e32 v73, v64
	v_mov_b32_e32 v74, v64
	v_mov_b32_e32 v75, v64
	v_mov_b32_e32 v76, v64
	v_mov_b32_e32 v77, v64
	v_mov_b32_e32 v78, v64
	v_mov_b32_e32 v79, v64
	v_mov_b32_e32 v88, v64
	v_mov_b32_e32 v89, v64
	v_mov_b32_e32 v90, v64
	v_mov_b32_e32 v91, v64
	v_mov_b32_e32 v92, v64
	v_mov_b32_e32 v93, v64
	v_mov_b32_e32 v94, v64
	v_mov_b32_e32 v95, v64
	v_mov_b32_e32 v106, v64
	v_mov_b32_e32 v107, v64
	v_mov_b32_e32 v108, v64
	v_mov_b32_e32 v109, v64
	v_mov_b32_e32 v110, v64
	v_mov_b32_e32 v111, v64
	v_mov_b32_e32 v112, v64
	v_mov_b32_e32 v113, v64
	v_mov_b32_e32 v130, v64
	v_mov_b32_e32 v131, v64
	v_mov_b32_e32 v132, v64
	v_mov_b32_e32 v133, v64
	v_mov_b32_e32 v134, v64
	v_mov_b32_e32 v135, v64
	v_mov_b32_e32 v136, v64
	v_mov_b32_e32 v137, v64
	v_add_u32_e32 v250, 0x10000, v222
	v_add_u32_e32 v251, 0x14000, v222
	v_add_u32_e32 v252, 0x18000, v222
	v_add_u32_e32 v253, 0x1c000, v222
	s_branch .LBB0_729

.LBB0_729:
	s_add_u32 s7, s54, s60
	s_addc_u32 s11, s55, s61
	s_add_u32 s7, s7, 0x100
	s_addc_u32 s11, s11, 0
	s_add_i32 s42, 0, 0x10000
	s_add_u32 s43, s81, s60
	s_addc_u32 s62, s10, s61
	s_cmpk_eq_i32 s60, 0xf00
	s_cselect_b64 s[66:67], -1, 0
	s_and_b64 s[26:27], s[66:67], exec
	s_cselect_b32 s65, s47, s11
	s_cselect_b32 s64, s46, s7
	s_cselect_b32 s63, s45, s62
	s_cselect_b32 s62, s80, s43
	s_add_i32 s7, 0, 0x14000
	ds_read_b128 v[154:157], v250
	ds_read_b128 v[158:161], v250 offset:1024
	ds_read_b128 v[162:165], v250 offset:2048
	ds_read_b128 v[166:169], v250 offset:3072
	ds_read_b128 v[138:141], v251
	ds_read_b128 v[142:145], v251 offset:1024
	ds_read_b128 v[146:149], v251 offset:2048
	ds_read_b128 v[150:153], v251 offset:3072
	s_waitcnt lgkmcnt(0)
	v_lshl_add_u64 v[122:123], v[212:213], 0, s[60:61]
	s_add_i32 m0, s39, 0xc000
	ds_read_b128 v[170:173], v224
	ds_read_b128 v[174:177], v224 offset:1024
	ds_read_b128 v[178:181], v224 offset:2048
	ds_read_b128 v[182:185], v224 offset:3072
	ds_read_b128 v[186:189], v224 offset:4096
	ds_read_b128 v[190:193], v224 offset:5120
	ds_read_b128 v[214:217], v224 offset:6144
	ds_read_b128 v[218:221], v224 offset:7168
	global_load_lds_dwordx4 v[122:123], off
	v_lshl_add_u64 v[122:123], v[210:211], 0, s[60:61]
	s_add_i32 m0, s39, 0xe000
	s_nop 0
	global_load_lds_dwordx4 v[122:123], off
	s_waitcnt vmcnt(8)
	s_waitcnt lgkmcnt(0)
	s_barrier
	s_setprio 1
	s_waitcnt lgkmcnt(0)
	v_mfma_f32_16x16x32_bf16 v[122:125], v[154:157], v[170:173], v[134:137]
	v_mfma_f32_16x16x32_bf16 v[126:129], v[162:165], v[170:173], v[130:133]
	v_mfma_f32_16x16x32_bf16 v[110:113], v[154:157], v[178:181], v[110:113]
	v_mfma_f32_16x16x32_bf16 v[106:109], v[162:165], v[178:181], v[106:109]
	v_mfma_f32_16x16x32_bf16 v[92:95], v[154:157], v[186:189], v[92:95]
	v_mfma_f32_16x16x32_bf16 v[88:91], v[162:165], v[186:189], v[88:91]
	v_mfma_f32_16x16x32_bf16 v[76:79], v[154:157], v[214:217], v[76:79]
	v_mfma_f32_16x16x32_bf16 v[72:75], v[162:165], v[214:217], v[72:75]
	v_mfma_f32_16x16x32_bf16 v[122:125], v[158:161], v[174:177], v[122:125]
	v_mfma_f32_16x16x32_bf16 v[126:129], v[166:169], v[174:177], v[126:129]
	v_mfma_f32_16x16x32_bf16 v[110:113], v[158:161], v[182:185], v[110:113]
	v_mfma_f32_16x16x32_bf16 v[106:109], v[166:169], v[182:185], v[106:109]
	v_mfma_f32_16x16x32_bf16 v[92:95], v[158:161], v[190:193], v[92:95]
	v_mfma_f32_16x16x32_bf16 v[88:91], v[166:169], v[190:193], v[88:91]
	v_mfma_f32_16x16x32_bf16 v[76:79], v[158:161], v[218:221], v[76:79]
	v_mfma_f32_16x16x32_bf16 v[72:75], v[166:169], v[218:221], v[72:75]
	s_setprio 0
	s_setprio 1
	v_mfma_f32_16x16x32_bf16 v[118:121], v[138:141], v[170:173], v[118:121]
	v_mfma_f32_16x16x32_bf16 v[114:117], v[146:149], v[170:173], v[114:117]
	v_mfma_f32_16x16x32_bf16 v[102:105], v[138:141], v[178:181], v[102:105]
	v_mfma_f32_16x16x32_bf16 v[98:101], v[146:149], v[178:181], v[98:101]
	v_mfma_f32_16x16x32_bf16 v[84:87], v[138:141], v[186:189], v[84:87]
	v_mfma_f32_16x16x32_bf16 v[80:83], v[146:149], v[186:189], v[80:83]
	v_mfma_f32_16x16x32_bf16 v[68:71], v[138:141], v[214:217], v[68:71]
	v_mfma_f32_16x16x32_bf16 v[64:67], v[146:149], v[214:217], v[64:67]
	v_mfma_f32_16x16x32_bf16 v[118:121], v[142:145], v[174:177], v[118:121]
	v_mfma_f32_16x16x32_bf16 v[114:117], v[150:153], v[174:177], v[114:117]
	v_mfma_f32_16x16x32_bf16 v[102:105], v[142:145], v[182:185], v[102:105]
	v_mfma_f32_16x16x32_bf16 v[98:101], v[150:153], v[182:185], v[98:101]
	v_mfma_f32_16x16x32_bf16 v[84:87], v[142:145], v[190:193], v[84:87]
	v_mfma_f32_16x16x32_bf16 v[80:83], v[150:153], v[190:193], v[80:83]
	v_mfma_f32_16x16x32_bf16 v[68:71], v[142:145], v[218:221], v[68:71]
	v_mfma_f32_16x16x32_bf16 v[64:67], v[150:153], v[218:221], v[64:67]
	s_setprio 0
	s_barrier
	s_add_i32 s11, s42, s38
	s_mov_b32 m0, s11
	ds_read_b128 v[186:189], v224 offset:16384
	ds_read_b128 v[190:193], v224 offset:17408
	ds_read_b128 v[178:181], v224 offset:18432
	ds_read_b128 v[182:185], v224 offset:19456
	ds_read_b128 v[170:173], v224 offset:20480
	ds_read_b128 v[174:177], v224 offset:21504
	ds_read_b128 v[130:133], v224 offset:22528
	ds_read_b128 v[134:137], v224 offset:23552
	global_load_lds_dwordx4 v200, s[62:63]
	s_add_i32 m0, s11, 0x2000
	s_add_u32 s26, s62, 0x80000
	s_addc_u32 s27, s63, 0
	s_add_i32 s7, s7, s38
	global_load_lds_dwordx4 v204, s[62:63]
	s_mov_b32 m0, s7
	s_nop 0
	global_load_lds_dwordx4 v200, s[26:27]
	s_add_i32 m0, s7, 0x2000
	s_nop 0
	global_load_lds_dwordx4 v204, s[26:27]
	s_mov_b32 m0, s39
	s_andn2_b64 s[42:43], exec, s[58:59]
	global_load_lds_dwordx4 v198, s[64:65]
	s_mov_b32 m0, s51
	s_andn2_b64 vcc, exec, s[58:59]
	global_load_lds_dwordx4 v202, s[64:65]
	s_waitcnt vmcnt(8)
	s_waitcnt lgkmcnt(0)
	s_barrier
	s_cbranch_vccnz .LBB0_731
	s_setprio 1
	s_waitcnt lgkmcnt(0)
	v_mfma_f32_16x16x32_bf16 v[60:63], v[154:157], v[186:189], v[60:63]
	v_mfma_f32_16x16x32_bf16 v[56:59], v[162:165], v[186:189], v[56:59]
	v_mfma_f32_16x16x32_bf16 v[44:47], v[154:157], v[178:181], v[44:47]
	v_mfma_f32_16x16x32_bf16 v[40:43], v[162:165], v[178:181], v[40:43]
	v_mfma_f32_16x16x32_bf16 v[28:31], v[154:157], v[170:173], v[28:31]
	v_mfma_f32_16x16x32_bf16 v[24:27], v[162:165], v[170:173], v[24:27]
	v_mfma_f32_16x16x32_bf16 v[12:15], v[154:157], v[130:133], v[12:15]
	v_mfma_f32_16x16x32_bf16 v[8:11], v[162:165], v[130:133], v[8:11]
	v_mfma_f32_16x16x32_bf16 v[60:63], v[158:161], v[190:193], v[60:63]
	v_mfma_f32_16x16x32_bf16 v[56:59], v[166:169], v[190:193], v[56:59]
	v_mfma_f32_16x16x32_bf16 v[44:47], v[158:161], v[182:185], v[44:47]
	v_mfma_f32_16x16x32_bf16 v[40:43], v[166:169], v[182:185], v[40:43]
	v_mfma_f32_16x16x32_bf16 v[28:31], v[158:161], v[174:177], v[28:31]
	v_mfma_f32_16x16x32_bf16 v[24:27], v[166:169], v[174:177], v[24:27]
	v_mfma_f32_16x16x32_bf16 v[12:15], v[158:161], v[134:137], v[12:15]
	v_mfma_f32_16x16x32_bf16 v[8:11], v[166:169], v[134:137], v[8:11]
	s_setprio 0
	s_setprio 1
	v_mfma_f32_16x16x32_bf16 v[52:55], v[138:141], v[186:189], v[52:55]
	v_mfma_f32_16x16x32_bf16 v[48:51], v[146:149], v[186:189], v[48:51]
	v_mfma_f32_16x16x32_bf16 v[36:39], v[138:141], v[178:181], v[36:39]
	v_mfma_f32_16x16x32_bf16 v[32:35], v[146:149], v[178:181], v[32:35]
	v_mfma_f32_16x16x32_bf16 v[20:23], v[138:141], v[170:173], v[20:23]
	v_mfma_f32_16x16x32_bf16 v[16:19], v[146:149], v[170:173], v[16:19]
	v_mfma_f32_16x16x32_bf16 v[4:7], v[138:141], v[130:133], v[4:7]
	v_mfma_f32_16x16x32_bf16 v[0:3], v[146:149], v[130:133], v[0:3]
	v_mfma_f32_16x16x32_bf16 v[52:55], v[142:145], v[190:193], v[52:55]
	v_mfma_f32_16x16x32_bf16 v[48:51], v[150:153], v[190:193], v[48:51]
	v_mfma_f32_16x16x32_bf16 v[36:39], v[142:145], v[182:185], v[36:39]
	v_mfma_f32_16x16x32_bf16 v[32:35], v[150:153], v[182:185], v[32:35]
	v_mfma_f32_16x16x32_bf16 v[20:23], v[142:145], v[174:177], v[20:23]
	v_mfma_f32_16x16x32_bf16 v[16:19], v[150:153], v[174:177], v[16:19]
	v_mfma_f32_16x16x32_bf16 v[4:7], v[142:145], v[134:137], v[4:7]
	v_mfma_f32_16x16x32_bf16 v[0:3], v[150:153], v[134:137], v[0:3]
	s_setprio 0
.LBB0_731:
	s_and_b64 s[26:27], s[56:57], s[66:67]
	s_and_b64 s[26:27], s[26:27], exec
	s_cselect_b32 s7, 0, s53
	s_cselect_b32 s11, s4, s52
	s_barrier
	s_add_i32 s66, 0, 0x18000
	s_add_i32 s67, 0, 0x1c000
	ds_read_b128 v[154:157], v252
	ds_read_b128 v[158:161], v252 offset:1024
	ds_read_b128 v[162:165], v252 offset:2048
	ds_read_b128 v[166:169], v252 offset:3072
	ds_read_b128 v[138:141], v253
	ds_read_b128 v[142:145], v253 offset:1024
	ds_read_b128 v[146:149], v253 offset:2048
	ds_read_b128 v[150:153], v253 offset:3072
	s_add_u32 s26, s64, s11
	s_addc_u32 s27, s65, s7
	s_mov_b32 m0, s69
	s_waitcnt lgkmcnt(0)
	ds_read_b128 v[170:173], v224 offset:32768
	ds_read_b128 v[174:177], v224 offset:33792
	ds_read_b128 v[178:181], v224 offset:34816
	ds_read_b128 v[182:185], v224 offset:35840
	ds_read_b128 v[186:189], v224 offset:36864
	ds_read_b128 v[190:193], v224 offset:37888
	ds_read_b128 v[226:229], v224 offset:38912
	ds_read_b128 v[230:233], v224 offset:39936
	global_load_lds_dwordx4 v198, s[26:27]
	s_mov_b32 m0, s70
	s_nop 0
	global_load_lds_dwordx4 v202, s[26:27]
	s_waitcnt vmcnt(8)
	s_waitcnt lgkmcnt(0)
	s_barrier
	s_setprio 1
	s_waitcnt lgkmcnt(0)
	v_mfma_f32_16x16x32_bf16 v[122:125], v[154:157], v[170:173], v[122:125]
	v_mfma_f32_16x16x32_bf16 v[134:137], v[158:161], v[174:177], v[122:125]
	v_mfma_f32_16x16x32_bf16 v[122:125], v[162:165], v[170:173], v[126:129]
	v_mfma_f32_16x16x32_bf16 v[110:113], v[154:157], v[178:181], v[110:113]
	v_mfma_f32_16x16x32_bf16 v[106:109], v[162:165], v[178:181], v[106:109]
	v_mfma_f32_16x16x32_bf16 v[92:95], v[154:157], v[186:189], v[92:95]
	v_mfma_f32_16x16x32_bf16 v[88:91], v[162:165], v[186:189], v[88:91]
	v_mfma_f32_16x16x32_bf16 v[76:79], v[154:157], v[226:229], v[76:79]
	v_mfma_f32_16x16x32_bf16 v[72:75], v[162:165], v[226:229], v[72:75]
	v_mfma_f32_16x16x32_bf16 v[130:133], v[166:169], v[174:177], v[122:125]
	v_mfma_f32_16x16x32_bf16 v[110:113], v[158:161], v[182:185], v[110:113]
	v_mfma_f32_16x16x32_bf16 v[106:109], v[166:169], v[182:185], v[106:109]
	v_mfma_f32_16x16x32_bf16 v[92:95], v[158:161], v[190:193], v[92:95]
	v_mfma_f32_16x16x32_bf16 v[88:91], v[166:169], v[190:193], v[88:91]
	v_mfma_f32_16x16x32_bf16 v[76:79], v[158:161], v[230:233], v[76:79]
	v_mfma_f32_16x16x32_bf16 v[72:75], v[166:169], v[230:233], v[72:75]
	s_setprio 0
	s_setprio 1
	v_mfma_f32_16x16x32_bf16 v[118:121], v[138:141], v[170:173], v[118:121]
	v_mfma_f32_16x16x32_bf16 v[114:117], v[146:149], v[170:173], v[114:117]
	v_mfma_f32_16x16x32_bf16 v[102:105], v[138:141], v[178:181], v[102:105]
	v_mfma_f32_16x16x32_bf16 v[98:101], v[146:149], v[178:181], v[98:101]
	v_mfma_f32_16x16x32_bf16 v[84:87], v[138:141], v[186:189], v[84:87]
	v_mfma_f32_16x16x32_bf16 v[80:83], v[146:149], v[186:189], v[80:83]
	v_mfma_f32_16x16x32_bf16 v[68:71], v[138:141], v[226:229], v[68:71]
	v_mfma_f32_16x16x32_bf16 v[64:67], v[146:149], v[226:229], v[64:67]
	v_mfma_f32_16x16x32_bf16 v[118:121], v[142:145], v[174:177], v[118:121]
	v_mfma_f32_16x16x32_bf16 v[114:117], v[150:153], v[174:177], v[114:117]
	v_mfma_f32_16x16x32_bf16 v[102:105], v[142:145], v[182:185], v[102:105]
	v_mfma_f32_16x16x32_bf16 v[98:101], v[150:153], v[182:185], v[98:101]
	v_mfma_f32_16x16x32_bf16 v[84:87], v[142:145], v[190:193], v[84:87]
	v_mfma_f32_16x16x32_bf16 v[80:83], v[150:153], v[190:193], v[80:83]
	v_mfma_f32_16x16x32_bf16 v[68:71], v[142:145], v[230:233], v[68:71]
	v_mfma_f32_16x16x32_bf16 v[64:67], v[150:153], v[230:233], v[64:67]
	s_setprio 0
	s_barrier
	s_add_i32 s7, s66, s38
	s_add_i32 m0, s7, 0xffffff80
	ds_read_b128 v[186:189], v224 offset:49152
	ds_read_b128 v[190:193], v224 offset:50176
	ds_read_b128 v[178:181], v224 offset:51200
	ds_read_b128 v[182:185], v224 offset:52224
	ds_read_b128 v[170:173], v224 offset:53248
	ds_read_b128 v[174:177], v224 offset:54272
	ds_read_b128 v[122:125], v224 offset:55296
	ds_read_b128 v[126:129], v224 offset:56320
	global_load_lds_dwordx4 v200, s[62:63] offset:128
	s_add_i32 m0, s7, 0x1f80
	s_add_u32 s26, s62, 0x80080
	s_addc_u32 s27, s63, 0
	s_add_i32 s7, s67, s38
	global_load_lds_dwordx4 v204, s[62:63] offset:128
	s_mov_b32 m0, s7
	s_and_b64 vcc, exec, s[42:43]
	global_load_lds_dwordx4 v200, s[26:27]
	s_add_i32 m0, s7, 0x2000
	s_nop 0
	global_load_lds_dwordx4 v204, s[26:27]
	s_add_i32 m0, s71, 0xffffff80
	s_nop 0
	global_load_lds_dwordx4 v198, s[64:65] offset:128
	s_add_i32 m0, s72, 0xffffff80
	s_nop 0
	global_load_lds_dwordx4 v202, s[64:65] offset:128
	s_waitcnt vmcnt(8)
	s_waitcnt lgkmcnt(0)
	s_barrier
	s_cbranch_vccnz .LBB0_728
	s_setprio 1
	s_waitcnt lgkmcnt(0)
	v_mfma_f32_16x16x32_bf16 v[60:63], v[154:157], v[186:189], v[60:63]
	v_mfma_f32_16x16x32_bf16 v[56:59], v[162:165], v[186:189], v[56:59]
	v_mfma_f32_16x16x32_bf16 v[44:47], v[154:157], v[178:181], v[44:47]
	v_mfma_f32_16x16x32_bf16 v[40:43], v[162:165], v[178:181], v[40:43]
	v_mfma_f32_16x16x32_bf16 v[28:31], v[154:157], v[170:173], v[28:31]
	v_mfma_f32_16x16x32_bf16 v[24:27], v[162:165], v[170:173], v[24:27]
	v_mfma_f32_16x16x32_bf16 v[12:15], v[154:157], v[122:125], v[12:15]
	v_mfma_f32_16x16x32_bf16 v[8:11], v[162:165], v[122:125], v[8:11]
	v_mfma_f32_16x16x32_bf16 v[60:63], v[158:161], v[190:193], v[60:63]
	v_mfma_f32_16x16x32_bf16 v[56:59], v[166:169], v[190:193], v[56:59]
	v_mfma_f32_16x16x32_bf16 v[44:47], v[158:161], v[182:185], v[44:47]
	v_mfma_f32_16x16x32_bf16 v[40:43], v[166:169], v[182:185], v[40:43]
	v_mfma_f32_16x16x32_bf16 v[28:31], v[158:161], v[174:177], v[28:31]
	v_mfma_f32_16x16x32_bf16 v[24:27], v[166:169], v[174:177], v[24:27]
	v_mfma_f32_16x16x32_bf16 v[12:15], v[158:161], v[126:129], v[12:15]
	v_mfma_f32_16x16x32_bf16 v[8:11], v[166:169], v[126:129], v[8:11]
	s_setprio 0
	s_setprio 1
	v_mfma_f32_16x16x32_bf16 v[52:55], v[138:141], v[186:189], v[52:55]
	v_mfma_f32_16x16x32_bf16 v[48:51], v[146:149], v[186:189], v[48:51]
	v_mfma_f32_16x16x32_bf16 v[36:39], v[138:141], v[178:181], v[36:39]
	v_mfma_f32_16x16x32_bf16 v[32:35], v[146:149], v[178:181], v[32:35]
	v_mfma_f32_16x16x32_bf16 v[20:23], v[138:141], v[170:173], v[20:23]
	v_mfma_f32_16x16x32_bf16 v[16:19], v[146:149], v[170:173], v[16:19]
	v_mfma_f32_16x16x32_bf16 v[4:7], v[138:141], v[122:125], v[4:7]
	v_mfma_f32_16x16x32_bf16 v[0:3], v[146:149], v[122:125], v[0:3]
	v_mfma_f32_16x16x32_bf16 v[52:55], v[142:145], v[190:193], v[52:55]
	v_mfma_f32_16x16x32_bf16 v[48:51], v[150:153], v[190:193], v[48:51]
	v_mfma_f32_16x16x32_bf16 v[36:39], v[142:145], v[182:185], v[36:39]
	v_mfma_f32_16x16x32_bf16 v[32:35], v[150:153], v[182:185], v[32:35]
	v_mfma_f32_16x16x32_bf16 v[20:23], v[142:145], v[174:177], v[20:23]
	v_mfma_f32_16x16x32_bf16 v[16:19], v[150:153], v[174:177], v[16:19]
	v_mfma_f32_16x16x32_bf16 v[4:7], v[142:145], v[126:129], v[4:7]
	v_mfma_f32_16x16x32_bf16 v[0:3], v[150:153], v[126:129], v[0:3]
	s_setprio 0
	s_branch .LBB0_728

.LBB0_767:
	s_cmp_eq_u32 s77, 2
	s_cselect_b32 s4, 0x4c0000, 0
	s_cmp_eq_u32 s78, 2
	s_cselect_b64 s[56:57], -1, 0
	s_ashr_i32 s19, s18, 31
	s_lshl_b64 s[6:7], s[18:19], 20
	s_add_u32 s46, s38, s6
	s_addc_u32 s47, s39, s7
	s_and_b64 s[6:7], s[54:55], exec
	s_cselect_b32 s19, s47, s43
	s_cselect_b32 s80, s46, s42
	s_add_u32 s6, s52, 0x80
	s_addc_u32 s7, s53, 0
	v_lshl_add_u64 v[0:1], s[6:7], 0, v[206:207]
	v_lshl_add_u64 v[210:211], v[0:1], 0, s[50:51]
	v_lshl_add_u64 v[0:1], s[6:7], 0, v[208:209]
	v_mov_b32_e32 v97, v96
	v_lshl_add_u64 v[212:213], v[0:1], 0, s[50:51]
	s_add_u32 s81, s42, 0x100
	v_mov_b32_e32 v98, v96
	v_mov_b32_e32 v99, v96
	v_mov_b32_e32 v64, 0
	v_mov_b64_e32 v[0:1], v[96:97]
	v_mov_b64_e32 v[4:5], v[96:97]
	v_mov_b64_e32 v[16:17], v[96:97]
	v_mov_b64_e32 v[20:21], v[96:97]
	v_mov_b64_e32 v[32:33], v[96:97]
	v_mov_b64_e32 v[36:37], v[96:97]
	v_mov_b64_e32 v[48:49], v[96:97]
	v_mov_b64_e32 v[52:53], v[96:97]
	v_mov_b64_e32 v[8:9], v[96:97]
	v_mov_b64_e32 v[12:13], v[96:97]
	v_mov_b64_e32 v[24:25], v[96:97]
	v_mov_b64_e32 v[28:29], v[96:97]
	v_mov_b64_e32 v[40:41], v[96:97]
	v_mov_b64_e32 v[44:45], v[96:97]
	v_mov_b64_e32 v[56:57], v[96:97]
	v_mov_b64_e32 v[60:61], v[96:97]
	s_addc_u32 s6, s43, 0
	s_mov_b32 s7, -2
	s_mov_b64 s[58:59], 0
	v_mov_b64_e32 v[2:3], v[98:99]
	v_mov_b64_e32 v[6:7], v[98:99]
	v_mov_b64_e32 v[18:19], v[98:99]
	v_mov_b64_e32 v[22:23], v[98:99]
	v_mov_b64_e32 v[34:35], v[98:99]
	v_mov_b64_e32 v[38:39], v[98:99]
	v_mov_b64_e32 v[50:51], v[98:99]
	v_mov_b64_e32 v[54:55], v[98:99]
	v_mov_b64_e32 v[10:11], v[98:99]
	v_mov_b64_e32 v[14:15], v[98:99]
	v_mov_b64_e32 v[26:27], v[98:99]
	v_mov_b64_e32 v[30:31], v[98:99]
	v_mov_b64_e32 v[42:43], v[98:99]
	v_mov_b64_e32 v[46:47], v[98:99]
	v_mov_b64_e32 v[58:59], v[98:99]
	v_mov_b64_e32 v[62:63], v[98:99]
	v_mov_b32_e32 v65, v64
	v_mov_b32_e32 v66, v64
	v_mov_b32_e32 v67, v64
	v_mov_b32_e32 v68, v64
	v_mov_b32_e32 v69, v64
	v_mov_b32_e32 v70, v64
	v_mov_b32_e32 v71, v64
	v_mov_b32_e32 v80, v64
	v_mov_b32_e32 v81, v64
	v_mov_b32_e32 v82, v64
	v_mov_b32_e32 v83, v64
	v_mov_b32_e32 v84, v64
	v_mov_b32_e32 v85, v64
	v_mov_b32_e32 v86, v64
	v_mov_b32_e32 v87, v64
	v_mov_b32_e32 v98, v64
	v_mov_b32_e32 v99, v64
	v_mov_b32_e32 v100, v64
	v_mov_b32_e32 v101, v64
	v_mov_b32_e32 v102, v64
	v_mov_b32_e32 v103, v64
	v_mov_b32_e32 v104, v64
	v_mov_b32_e32 v105, v64
	v_mov_b32_e32 v114, v64
	v_mov_b32_e32 v115, v64
	v_mov_b32_e32 v116, v64
	v_mov_b32_e32 v117, v64
	v_mov_b32_e32 v118, v64
	v_mov_b32_e32 v119, v64
	v_mov_b32_e32 v120, v64
	v_mov_b32_e32 v121, v64
	v_mov_b32_e32 v72, v64
	v_mov_b32_e32 v73, v64
	v_mov_b32_e32 v74, v64
	v_mov_b32_e32 v75, v64
	v_mov_b32_e32 v76, v64
	v_mov_b32_e32 v77, v64
	v_mov_b32_e32 v78, v64
	v_mov_b32_e32 v79, v64
	v_mov_b32_e32 v88, v64
	v_mov_b32_e32 v89, v64
	v_mov_b32_e32 v90, v64
	v_mov_b32_e32 v91, v64
	v_mov_b32_e32 v92, v64
	v_mov_b32_e32 v93, v64
	v_mov_b32_e32 v94, v64
	v_mov_b32_e32 v95, v64
	v_mov_b32_e32 v106, v64
	v_mov_b32_e32 v107, v64
	v_mov_b32_e32 v108, v64
	v_mov_b32_e32 v109, v64
	v_mov_b32_e32 v110, v64
	v_mov_b32_e32 v111, v64
	v_mov_b32_e32 v112, v64
	v_mov_b32_e32 v113, v64
	v_mov_b32_e32 v130, v64
	v_mov_b32_e32 v131, v64
	v_mov_b32_e32 v132, v64
	v_mov_b32_e32 v133, v64
	v_mov_b32_e32 v134, v64
	v_mov_b32_e32 v135, v64
	v_mov_b32_e32 v136, v64
	v_mov_b32_e32 v137, v64
	v_add_u32_e32 v250, 0x14000, v222
	v_add_u32_e32 v251, 0x18000, v222
	v_add_u32_e32 v252, 0x1c000, v222
	s_branch .LBB0_769

.LBB0_769:
	s_add_u32 s26, s52, s58
	s_addc_u32 s27, s53, s59
	s_add_u32 s42, s26, 0x100
	s_addc_u32 s43, s27, 0
	s_add_i32 vcc_lo, 0, 0x10000
	s_add_u32 s60, s81, s58
	s_addc_u32 s61, s6, s59
	s_cmpk_eq_i32 s58, 0xf00
	s_cselect_b64 s[64:65], -1, 0
	s_and_b64 s[26:27], s[64:65], exec
	s_cselect_b32 s63, s45, s43
	s_cselect_b32 s62, s44, s42
	v_add_u32_e32 v97, vcc_lo, v222
	s_cselect_b32 s61, s19, s61
	s_cselect_b32 s60, s80, s60
	s_add_i32 s42, 0, 0x14000
	ds_read_b128 v[154:157], v97
	ds_read_b128 v[158:161], v97 offset:1024
	ds_read_b128 v[162:165], v97 offset:2048
	ds_read_b128 v[166:169], v97 offset:3072
	ds_read_b128 v[138:141], v250
	ds_read_b128 v[142:145], v250 offset:1024
	ds_read_b128 v[146:149], v250 offset:2048
	ds_read_b128 v[150:153], v250 offset:3072
	s_waitcnt lgkmcnt(0)
	v_lshl_add_u64 v[122:123], v[212:213], 0, s[58:59]
	s_add_i32 m0, s49, 0xc000
	ds_read_b128 v[170:173], v224
	ds_read_b128 v[174:177], v224 offset:1024
	ds_read_b128 v[178:181], v224 offset:2048
	ds_read_b128 v[182:185], v224 offset:3072
	ds_read_b128 v[186:189], v224 offset:4096
	ds_read_b128 v[190:193], v224 offset:5120
	ds_read_b128 v[214:217], v224 offset:6144
	ds_read_b128 v[218:221], v224 offset:7168
	global_load_lds_dwordx4 v[122:123], off
	v_lshl_add_u64 v[122:123], v[210:211], 0, s[58:59]
	s_add_i32 m0, s49, 0xe000
	s_nop 0
	global_load_lds_dwordx4 v[122:123], off
	s_waitcnt vmcnt(8)
	s_waitcnt lgkmcnt(0)
	s_barrier
	s_setprio 1
	s_waitcnt lgkmcnt(0)
	v_mfma_f32_16x16x32_bf16 v[122:125], v[154:157], v[170:173], v[134:137]
	v_mfma_f32_16x16x32_bf16 v[126:129], v[162:165], v[170:173], v[130:133]
	v_mfma_f32_16x16x32_bf16 v[110:113], v[154:157], v[178:181], v[110:113]
	v_mfma_f32_16x16x32_bf16 v[106:109], v[162:165], v[178:181], v[106:109]
	v_mfma_f32_16x16x32_bf16 v[92:95], v[154:157], v[186:189], v[92:95]
	v_mfma_f32_16x16x32_bf16 v[88:91], v[162:165], v[186:189], v[88:91]
	v_mfma_f32_16x16x32_bf16 v[76:79], v[154:157], v[214:217], v[76:79]
	v_mfma_f32_16x16x32_bf16 v[72:75], v[162:165], v[214:217], v[72:75]
	v_mfma_f32_16x16x32_bf16 v[122:125], v[158:161], v[174:177], v[122:125]
	v_mfma_f32_16x16x32_bf16 v[126:129], v[166:169], v[174:177], v[126:129]
	v_mfma_f32_16x16x32_bf16 v[110:113], v[158:161], v[182:185], v[110:113]
	v_mfma_f32_16x16x32_bf16 v[106:109], v[166:169], v[182:185], v[106:109]
	v_mfma_f32_16x16x32_bf16 v[92:95], v[158:161], v[190:193], v[92:95]
	v_mfma_f32_16x16x32_bf16 v[88:91], v[166:169], v[190:193], v[88:91]
	v_mfma_f32_16x16x32_bf16 v[76:79], v[158:161], v[218:221], v[76:79]
	v_mfma_f32_16x16x32_bf16 v[72:75], v[166:169], v[218:221], v[72:75]
	s_setprio 0
	s_setprio 1
	v_mfma_f32_16x16x32_bf16 v[118:121], v[138:141], v[170:173], v[118:121]
	v_mfma_f32_16x16x32_bf16 v[114:117], v[146:149], v[170:173], v[114:117]
	v_mfma_f32_16x16x32_bf16 v[102:105], v[138:141], v[178:181], v[102:105]
	v_mfma_f32_16x16x32_bf16 v[98:101], v[146:149], v[178:181], v[98:101]
	v_mfma_f32_16x16x32_bf16 v[84:87], v[138:141], v[186:189], v[84:87]
	v_mfma_f32_16x16x32_bf16 v[80:83], v[146:149], v[186:189], v[80:83]
	v_mfma_f32_16x16x32_bf16 v[68:71], v[138:141], v[214:217], v[68:71]
	v_mfma_f32_16x16x32_bf16 v[64:67], v[146:149], v[214:217], v[64:67]
	v_mfma_f32_16x16x32_bf16 v[118:121], v[142:145], v[174:177], v[118:121]
	v_mfma_f32_16x16x32_bf16 v[114:117], v[150:153], v[174:177], v[114:117]
	v_mfma_f32_16x16x32_bf16 v[102:105], v[142:145], v[182:185], v[102:105]
	v_mfma_f32_16x16x32_bf16 v[98:101], v[150:153], v[182:185], v[98:101]
	v_mfma_f32_16x16x32_bf16 v[84:87], v[142:145], v[190:193], v[84:87]
	v_mfma_f32_16x16x32_bf16 v[80:83], v[150:153], v[190:193], v[80:83]
	v_mfma_f32_16x16x32_bf16 v[68:71], v[142:145], v[218:221], v[68:71]
	v_mfma_f32_16x16x32_bf16 v[64:67], v[150:153], v[218:221], v[64:67]
	s_setprio 0
	s_barrier
	s_add_i32 s26, vcc_lo, s66
	s_mov_b32 m0, s26
	ds_read_b128 v[186:189], v224 offset:16384
	ds_read_b128 v[190:193], v224 offset:17408
	ds_read_b128 v[178:181], v224 offset:18432
	ds_read_b128 v[182:185], v224 offset:19456
	ds_read_b128 v[170:173], v224 offset:20480
	ds_read_b128 v[174:177], v224 offset:21504
	ds_read_b128 v[130:133], v224 offset:22528
	ds_read_b128 v[134:137], v224 offset:23552
	global_load_lds_dwordx4 v200, s[60:61]
	s_add_i32 m0, s26, 0x2000
	s_add_u32 s26, s60, 0x80000
	s_addc_u32 s27, s61, 0
	s_add_i32 s42, s42, s66
	global_load_lds_dwordx4 v204, s[60:61]
	s_mov_b32 m0, s42
	s_nop 0
	global_load_lds_dwordx4 v200, s[26:27]
	s_add_i32 m0, s42, 0x2000
	s_nop 0
	global_load_lds_dwordx4 v204, s[26:27]
	s_mov_b32 m0, s49
	s_andn2_b64 s[42:43], exec, s[56:57]
	global_load_lds_dwordx4 v198, s[62:63]
	s_mov_b32 m0, s67
	s_andn2_b64 vcc, exec, s[56:57]
	global_load_lds_dwordx4 v202, s[62:63]
	s_waitcnt vmcnt(8)
	s_waitcnt lgkmcnt(0)
	s_barrier
	s_cbranch_vccnz .LBB0_771
	s_setprio 1
	s_waitcnt lgkmcnt(0)
	v_mfma_f32_16x16x32_bf16 v[60:63], v[154:157], v[186:189], v[60:63]
	v_mfma_f32_16x16x32_bf16 v[56:59], v[162:165], v[186:189], v[56:59]
	v_mfma_f32_16x16x32_bf16 v[44:47], v[154:157], v[178:181], v[44:47]
	v_mfma_f32_16x16x32_bf16 v[40:43], v[162:165], v[178:181], v[40:43]
	v_mfma_f32_16x16x32_bf16 v[28:31], v[154:157], v[170:173], v[28:31]
	v_mfma_f32_16x16x32_bf16 v[24:27], v[162:165], v[170:173], v[24:27]
	v_mfma_f32_16x16x32_bf16 v[12:15], v[154:157], v[130:133], v[12:15]
	v_mfma_f32_16x16x32_bf16 v[8:11], v[162:165], v[130:133], v[8:11]
	v_mfma_f32_16x16x32_bf16 v[60:63], v[158:161], v[190:193], v[60:63]
	v_mfma_f32_16x16x32_bf16 v[56:59], v[166:169], v[190:193], v[56:59]
	v_mfma_f32_16x16x32_bf16 v[44:47], v[158:161], v[182:185], v[44:47]
	v_mfma_f32_16x16x32_bf16 v[40:43], v[166:169], v[182:185], v[40:43]
	v_mfma_f32_16x16x32_bf16 v[28:31], v[158:161], v[174:177], v[28:31]
	v_mfma_f32_16x16x32_bf16 v[24:27], v[166:169], v[174:177], v[24:27]
	v_mfma_f32_16x16x32_bf16 v[12:15], v[158:161], v[134:137], v[12:15]
	v_mfma_f32_16x16x32_bf16 v[8:11], v[166:169], v[134:137], v[8:11]
	s_setprio 0
	s_setprio 1
	v_mfma_f32_16x16x32_bf16 v[52:55], v[138:141], v[186:189], v[52:55]
	v_mfma_f32_16x16x32_bf16 v[48:51], v[146:149], v[186:189], v[48:51]
	v_mfma_f32_16x16x32_bf16 v[36:39], v[138:141], v[178:181], v[36:39]
	v_mfma_f32_16x16x32_bf16 v[32:35], v[146:149], v[178:181], v[32:35]
	v_mfma_f32_16x16x32_bf16 v[20:23], v[138:141], v[170:173], v[20:23]
	v_mfma_f32_16x16x32_bf16 v[16:19], v[146:149], v[170:173], v[16:19]
	v_mfma_f32_16x16x32_bf16 v[4:7], v[138:141], v[130:133], v[4:7]
	v_mfma_f32_16x16x32_bf16 v[0:3], v[146:149], v[130:133], v[0:3]
	v_mfma_f32_16x16x32_bf16 v[52:55], v[142:145], v[190:193], v[52:55]
	v_mfma_f32_16x16x32_bf16 v[48:51], v[150:153], v[190:193], v[48:51]
	v_mfma_f32_16x16x32_bf16 v[36:39], v[142:145], v[182:185], v[36:39]
	v_mfma_f32_16x16x32_bf16 v[32:35], v[150:153], v[182:185], v[32:35]
	v_mfma_f32_16x16x32_bf16 v[20:23], v[142:145], v[174:177], v[20:23]
	v_mfma_f32_16x16x32_bf16 v[16:19], v[150:153], v[174:177], v[16:19]
	v_mfma_f32_16x16x32_bf16 v[4:7], v[142:145], v[134:137], v[4:7]
	v_mfma_f32_16x16x32_bf16 v[0:3], v[150:153], v[134:137], v[0:3]
	s_setprio 0
.LBB0_771:
	s_and_b64 s[26:27], s[54:55], s[64:65]
	s_and_b64 s[26:27], s[26:27], exec
	s_cselect_b32 s27, 0, s51
	s_cselect_b32 s26, s4, s50
	s_barrier
	s_add_i32 s64, 0, 0x18000
	s_add_i32 s65, 0, 0x1c000
	ds_read_b128 v[154:157], v251
	ds_read_b128 v[158:161], v251 offset:1024
	ds_read_b128 v[162:165], v251 offset:2048
	ds_read_b128 v[166:169], v251 offset:3072
	ds_read_b128 v[138:141], v252
	ds_read_b128 v[142:145], v252 offset:1024
	ds_read_b128 v[146:149], v252 offset:2048
	ds_read_b128 v[150:153], v252 offset:3072
	s_add_u32 s26, s62, s26
	s_addc_u32 s27, s63, s27
	s_mov_b32 m0, s69
	s_waitcnt lgkmcnt(0)
	ds_read_b128 v[170:173], v224 offset:32768
	ds_read_b128 v[174:177], v224 offset:33792
	ds_read_b128 v[178:181], v224 offset:34816
	ds_read_b128 v[182:185], v224 offset:35840
	ds_read_b128 v[186:189], v224 offset:36864
	ds_read_b128 v[190:193], v224 offset:37888
	ds_read_b128 v[226:229], v224 offset:38912
	ds_read_b128 v[230:233], v224 offset:39936
	global_load_lds_dwordx4 v198, s[26:27]
	s_mov_b32 m0, s70
	s_nop 0
	global_load_lds_dwordx4 v202, s[26:27]
	s_waitcnt vmcnt(8)
	s_waitcnt lgkmcnt(0)
	s_barrier
	s_setprio 1
	s_waitcnt lgkmcnt(0)
	v_mfma_f32_16x16x32_bf16 v[122:125], v[154:157], v[170:173], v[122:125]
	v_mfma_f32_16x16x32_bf16 v[134:137], v[158:161], v[174:177], v[122:125]
	v_mfma_f32_16x16x32_bf16 v[122:125], v[162:165], v[170:173], v[126:129]
	v_mfma_f32_16x16x32_bf16 v[110:113], v[154:157], v[178:181], v[110:113]
	v_mfma_f32_16x16x32_bf16 v[106:109], v[162:165], v[178:181], v[106:109]
	v_mfma_f32_16x16x32_bf16 v[92:95], v[154:157], v[186:189], v[92:95]
	v_mfma_f32_16x16x32_bf16 v[88:91], v[162:165], v[186:189], v[88:91]
	v_mfma_f32_16x16x32_bf16 v[76:79], v[154:157], v[226:229], v[76:79]
	v_mfma_f32_16x16x32_bf16 v[72:75], v[162:165], v[226:229], v[72:75]
	v_mfma_f32_16x16x32_bf16 v[130:133], v[166:169], v[174:177], v[122:125]
	v_mfma_f32_16x16x32_bf16 v[110:113], v[158:161], v[182:185], v[110:113]
	v_mfma_f32_16x16x32_bf16 v[106:109], v[166:169], v[182:185], v[106:109]
	v_mfma_f32_16x16x32_bf16 v[92:95], v[158:161], v[190:193], v[92:95]
	v_mfma_f32_16x16x32_bf16 v[88:91], v[166:169], v[190:193], v[88:91]
	v_mfma_f32_16x16x32_bf16 v[76:79], v[158:161], v[230:233], v[76:79]
	v_mfma_f32_16x16x32_bf16 v[72:75], v[166:169], v[230:233], v[72:75]
	s_setprio 0
	s_setprio 1
	v_mfma_f32_16x16x32_bf16 v[118:121], v[138:141], v[170:173], v[118:121]
	v_mfma_f32_16x16x32_bf16 v[114:117], v[146:149], v[170:173], v[114:117]
	v_mfma_f32_16x16x32_bf16 v[102:105], v[138:141], v[178:181], v[102:105]
	v_mfma_f32_16x16x32_bf16 v[98:101], v[146:149], v[178:181], v[98:101]
	v_mfma_f32_16x16x32_bf16 v[84:87], v[138:141], v[186:189], v[84:87]
	v_mfma_f32_16x16x32_bf16 v[80:83], v[146:149], v[186:189], v[80:83]
	v_mfma_f32_16x16x32_bf16 v[68:71], v[138:141], v[226:229], v[68:71]
	v_mfma_f32_16x16x32_bf16 v[64:67], v[146:149], v[226:229], v[64:67]
	v_mfma_f32_16x16x32_bf16 v[118:121], v[142:145], v[174:177], v[118:121]
	v_mfma_f32_16x16x32_bf16 v[114:117], v[150:153], v[174:177], v[114:117]
	v_mfma_f32_16x16x32_bf16 v[102:105], v[142:145], v[182:185], v[102:105]
	v_mfma_f32_16x16x32_bf16 v[98:101], v[150:153], v[182:185], v[98:101]
	v_mfma_f32_16x16x32_bf16 v[84:87], v[142:145], v[190:193], v[84:87]
	v_mfma_f32_16x16x32_bf16 v[80:83], v[150:153], v[190:193], v[80:83]
	v_mfma_f32_16x16x32_bf16 v[68:71], v[142:145], v[230:233], v[68:71]
	v_mfma_f32_16x16x32_bf16 v[64:67], v[150:153], v[230:233], v[64:67]
	s_setprio 0
	s_barrier
	s_add_i32 s26, s64, s66
	s_add_i32 m0, s26, 0xffffff80
	ds_read_b128 v[186:189], v224 offset:49152
	ds_read_b128 v[190:193], v224 offset:50176
	ds_read_b128 v[178:181], v224 offset:51200
	ds_read_b128 v[182:185], v224 offset:52224
	ds_read_b128 v[170:173], v224 offset:53248
	ds_read_b128 v[174:177], v224 offset:54272
	ds_read_b128 v[122:125], v224 offset:55296
	ds_read_b128 v[126:129], v224 offset:56320
	global_load_lds_dwordx4 v200, s[60:61] offset:128
	s_add_i32 m0, s26, 0x1f80
	s_add_u32 s26, s60, 0x80080
	s_addc_u32 s27, s61, 0
	s_add_i32 s100, s65, s66
	global_load_lds_dwordx4 v204, s[60:61] offset:128
	s_mov_b32 m0, s100
	s_and_b64 vcc, exec, s[42:43]
	global_load_lds_dwordx4 v200, s[26:27]
	s_add_i32 m0, s100, 0x2000
	s_nop 0
	global_load_lds_dwordx4 v204, s[26:27]
	s_add_i32 m0, s71, 0xffffff80
	s_nop 0
	global_load_lds_dwordx4 v198, s[62:63] offset:128
	s_add_i32 m0, s72, 0xffffff80
	s_nop 0
	global_load_lds_dwordx4 v202, s[62:63] offset:128
	s_waitcnt vmcnt(8)
	s_waitcnt lgkmcnt(0)
	s_barrier
	s_cbranch_vccnz .LBB0_768
	s_setprio 1
	s_waitcnt lgkmcnt(0)
	v_mfma_f32_16x16x32_bf16 v[60:63], v[154:157], v[186:189], v[60:63]
	v_mfma_f32_16x16x32_bf16 v[56:59], v[162:165], v[186:189], v[56:59]
	v_mfma_f32_16x16x32_bf16 v[44:47], v[154:157], v[178:181], v[44:47]
	v_mfma_f32_16x16x32_bf16 v[40:43], v[162:165], v[178:181], v[40:43]
	v_mfma_f32_16x16x32_bf16 v[28:31], v[154:157], v[170:173], v[28:31]
	v_mfma_f32_16x16x32_bf16 v[24:27], v[162:165], v[170:173], v[24:27]
	v_mfma_f32_16x16x32_bf16 v[12:15], v[154:157], v[122:125], v[12:15]
	v_mfma_f32_16x16x32_bf16 v[8:11], v[162:165], v[122:125], v[8:11]
	v_mfma_f32_16x16x32_bf16 v[60:63], v[158:161], v[190:193], v[60:63]
	v_mfma_f32_16x16x32_bf16 v[56:59], v[166:169], v[190:193], v[56:59]
	v_mfma_f32_16x16x32_bf16 v[44:47], v[158:161], v[182:185], v[44:47]
	v_mfma_f32_16x16x32_bf16 v[40:43], v[166:169], v[182:185], v[40:43]
	v_mfma_f32_16x16x32_bf16 v[28:31], v[158:161], v[174:177], v[28:31]
	v_mfma_f32_16x16x32_bf16 v[24:27], v[166:169], v[174:177], v[24:27]
	v_mfma_f32_16x16x32_bf16 v[12:15], v[158:161], v[126:129], v[12:15]
	v_mfma_f32_16x16x32_bf16 v[8:11], v[166:169], v[126:129], v[8:11]
	s_setprio 0
	s_setprio 1
	v_mfma_f32_16x16x32_bf16 v[52:55], v[138:141], v[186:189], v[52:55]
	v_mfma_f32_16x16x32_bf16 v[48:51], v[146:149], v[186:189], v[48:51]
	v_mfma_f32_16x16x32_bf16 v[36:39], v[138:141], v[178:181], v[36:39]
	v_mfma_f32_16x16x32_bf16 v[32:35], v[146:149], v[178:181], v[32:35]
	v_mfma_f32_16x16x32_bf16 v[20:23], v[138:141], v[170:173], v[20:23]
	v_mfma_f32_16x16x32_bf16 v[16:19], v[146:149], v[170:173], v[16:19]
	v_mfma_f32_16x16x32_bf16 v[4:7], v[138:141], v[122:125], v[4:7]
	v_mfma_f32_16x16x32_bf16 v[0:3], v[146:149], v[122:125], v[0:3]
	v_mfma_f32_16x16x32_bf16 v[52:55], v[142:145], v[190:193], v[52:55]
	v_mfma_f32_16x16x32_bf16 v[48:51], v[150:153], v[190:193], v[48:51]
	v_mfma_f32_16x16x32_bf16 v[36:39], v[142:145], v[182:185], v[36:39]
	v_mfma_f32_16x16x32_bf16 v[32:35], v[150:153], v[182:185], v[32:35]
	v_mfma_f32_16x16x32_bf16 v[20:23], v[142:145], v[174:177], v[20:23]
	v_mfma_f32_16x16x32_bf16 v[16:19], v[150:153], v[174:177], v[16:19]
	v_mfma_f32_16x16x32_bf16 v[4:7], v[142:145], v[126:129], v[4:7]
	v_mfma_f32_16x16x32_bf16 v[0:3], v[150:153], v[126:129], v[0:3]
	s_setprio 0
	s_branch .LBB0_768

.LBB0_875:
	s_add_u32 s38, s56, s60
	s_addc_u32 s39, s57, s61
	s_add_u32 s62, s38, 0x100
	s_addc_u32 s63, s39, 0
	s_add_i32 vcc_lo, 0, 0x10000
	s_add_u32 vcc_hi, s15, s60
	s_addc_u32 s89, s26, s61
	s_cmpk_eq_i32 s60, 0xf00
	s_cselect_b64 s[66:67], -1, 0
	s_and_b64 s[38:39], s[66:67], exec
	s_cselect_b32 s65, s17, s63
	s_cselect_b32 s64, s43, s62
	v_add_u32_e32 v97, vcc_lo, v195
	s_cselect_b32 s63, s41, s89
	s_cselect_b32 s62, s14, vcc_hi
	s_add_i32 s89, 0, 0x14000
	ds_read_b128 v[146:149], v97
	ds_read_b128 v[150:153], v97 offset:1024
	ds_read_b128 v[154:157], v97 offset:2048
	ds_read_b128 v[158:161], v97 offset:3072
	v_add_u32_e32 v97, s89, v195
	ds_read_b128 v[130:133], v97
	ds_read_b128 v[134:137], v97 offset:1024
	ds_read_b128 v[138:141], v97 offset:2048
	ds_read_b128 v[142:145], v97 offset:3072
	v_lshl_add_u64 v[230:231], v[228:229], 0, s[60:61]
	s_add_i32 m0, s51, 0xc000
	s_waitcnt lgkmcnt(0)
	ds_read_b128 v[162:165], v251
	ds_read_b128 v[166:169], v251 offset:1024
	ds_read_b128 v[170:173], v251 offset:2048
	ds_read_b128 v[174:177], v251 offset:3072
	ds_read_b128 v[178:181], v251 offset:4096
	ds_read_b128 v[182:185], v251 offset:5120
	ds_read_b128 v[186:189], v251 offset:6144
	ds_read_b128 v[190:193], v251 offset:7168
	global_load_lds_dwordx4 v[230:231], off
	v_lshl_add_u64 v[230:231], v[226:227], 0, s[60:61]
	s_add_i32 m0, s51, 0xe000
	s_nop 0
	global_load_lds_dwordx4 v[230:231], off
	s_waitcnt vmcnt(8)
	s_waitcnt lgkmcnt(0)
	s_barrier
	s_setprio 1
	s_waitcnt lgkmcnt(0)
	v_mfma_f32_16x16x32_bf16 v[126:129], v[146:149], v[162:165], v[126:129]
	v_mfma_f32_16x16x32_bf16 v[122:125], v[154:157], v[162:165], v[122:125]
	v_mfma_f32_16x16x32_bf16 v[118:121], v[146:149], v[170:173], v[118:121]
	v_mfma_f32_16x16x32_bf16 v[114:117], v[154:157], v[170:173], v[114:117]
	v_mfma_f32_16x16x32_bf16 v[110:113], v[146:149], v[178:181], v[110:113]
	v_mfma_f32_16x16x32_bf16 v[106:109], v[154:157], v[178:181], v[106:109]
	v_mfma_f32_16x16x32_bf16 v[102:105], v[146:149], v[186:189], v[102:105]
	v_mfma_f32_16x16x32_bf16 v[98:101], v[154:157], v[186:189], v[98:101]
	v_mfma_f32_16x16x32_bf16 v[126:129], v[150:153], v[166:169], v[126:129]
	v_mfma_f32_16x16x32_bf16 v[122:125], v[158:161], v[166:169], v[122:125]
	v_mfma_f32_16x16x32_bf16 v[118:121], v[150:153], v[174:177], v[118:121]
	v_mfma_f32_16x16x32_bf16 v[114:117], v[158:161], v[174:177], v[114:117]
	v_mfma_f32_16x16x32_bf16 v[110:113], v[150:153], v[182:185], v[110:113]
	v_mfma_f32_16x16x32_bf16 v[106:109], v[158:161], v[182:185], v[106:109]
	v_mfma_f32_16x16x32_bf16 v[102:105], v[150:153], v[190:193], v[102:105]
	v_mfma_f32_16x16x32_bf16 v[98:101], v[158:161], v[190:193], v[98:101]
	s_setprio 0
	s_setprio 1
	v_mfma_f32_16x16x32_bf16 v[92:95], v[130:133], v[162:165], v[92:95]
	v_mfma_f32_16x16x32_bf16 v[88:91], v[138:141], v[162:165], v[88:91]
	v_mfma_f32_16x16x32_bf16 v[84:87], v[130:133], v[170:173], v[84:87]
	v_mfma_f32_16x16x32_bf16 v[80:83], v[138:141], v[170:173], v[80:83]
	v_mfma_f32_16x16x32_bf16 v[76:79], v[130:133], v[178:181], v[76:79]
	v_mfma_f32_16x16x32_bf16 v[72:75], v[138:141], v[178:181], v[72:75]
	v_mfma_f32_16x16x32_bf16 v[64:67], v[130:133], v[186:189], v[64:67]
	v_mfma_f32_16x16x32_bf16 v[52:55], v[138:141], v[186:189], v[52:55]
	v_mfma_f32_16x16x32_bf16 v[92:95], v[134:137], v[166:169], v[92:95]
	v_mfma_f32_16x16x32_bf16 v[88:91], v[142:145], v[166:169], v[88:91]
	v_mfma_f32_16x16x32_bf16 v[84:87], v[134:137], v[174:177], v[84:87]
	v_mfma_f32_16x16x32_bf16 v[80:83], v[142:145], v[174:177], v[80:83]
	v_mfma_f32_16x16x32_bf16 v[76:79], v[134:137], v[182:185], v[76:79]
	v_mfma_f32_16x16x32_bf16 v[72:75], v[142:145], v[182:185], v[72:75]
	v_mfma_f32_16x16x32_bf16 v[64:67], v[134:137], v[190:193], v[64:67]
	v_mfma_f32_16x16x32_bf16 v[52:55], v[142:145], v[190:193], v[52:55]
	s_setprio 0
	s_barrier
	s_add_i32 s38, vcc_lo, s37
	s_mov_b32 m0, s38
	ds_read_b128 v[186:189], v251 offset:16384
	ds_read_b128 v[190:193], v251 offset:17408
	ds_read_b128 v[178:181], v251 offset:18432
	ds_read_b128 v[182:185], v251 offset:19456
	ds_read_b128 v[170:173], v251 offset:20480
	ds_read_b128 v[174:177], v251 offset:21504
	ds_read_b128 v[162:165], v251 offset:22528
	ds_read_b128 v[166:169], v251 offset:23552
	global_load_lds_dwordx4 v200, s[62:63]
	s_add_i32 m0, s38, 0x2000
	s_add_u32 s38, s62, 0x80000
	s_addc_u32 s39, s63, 0
	s_add_i32 s89, s89, s37
	global_load_lds_dwordx4 v204, s[62:63]
	s_mov_b32 m0, s89
	s_mov_b64 s[100:101], s[64:65]
	global_load_lds_dwordx4 v200, s[38:39]
	s_add_i32 m0, s89, 0x2000
	s_nop 0
	global_load_lds_dwordx4 v204, s[38:39]
	s_mov_b32 m0, s51
	s_andn2_b64 s[38:39], exec, s[58:59]
	global_load_lds_dwordx4 v198, s[100:101]
	s_mov_b32 m0, s53
	s_andn2_b64 vcc, exec, s[58:59]
	global_load_lds_dwordx4 v202, s[100:101]
	s_waitcnt vmcnt(8)
	s_waitcnt lgkmcnt(0)
	s_barrier
	s_cbranch_vccnz .LBB0_877
	s_setprio 1
	s_waitcnt lgkmcnt(0)
	v_mfma_f32_16x16x32_bf16 v[68:71], v[146:149], v[186:189], v[68:71]
	v_mfma_f32_16x16x32_bf16 v[60:63], v[154:157], v[186:189], v[60:63]
	v_mfma_f32_16x16x32_bf16 v[56:59], v[146:149], v[178:181], v[56:59]
	v_mfma_f32_16x16x32_bf16 v[48:51], v[154:157], v[178:181], v[48:51]
	v_mfma_f32_16x16x32_bf16 v[44:47], v[146:149], v[170:173], v[44:47]
	v_mfma_f32_16x16x32_bf16 v[40:43], v[154:157], v[170:173], v[40:43]
	v_mfma_f32_16x16x32_bf16 v[36:39], v[146:149], v[162:165], v[36:39]
	v_mfma_f32_16x16x32_bf16 v[32:35], v[154:157], v[162:165], v[32:35]
	v_mfma_f32_16x16x32_bf16 v[68:71], v[150:153], v[190:193], v[68:71]
	v_mfma_f32_16x16x32_bf16 v[60:63], v[158:161], v[190:193], v[60:63]
	v_mfma_f32_16x16x32_bf16 v[56:59], v[150:153], v[182:185], v[56:59]
	v_mfma_f32_16x16x32_bf16 v[48:51], v[158:161], v[182:185], v[48:51]
	v_mfma_f32_16x16x32_bf16 v[44:47], v[150:153], v[174:177], v[44:47]
	v_mfma_f32_16x16x32_bf16 v[40:43], v[158:161], v[174:177], v[40:43]
	v_mfma_f32_16x16x32_bf16 v[36:39], v[150:153], v[166:169], v[36:39]
	v_mfma_f32_16x16x32_bf16 v[32:35], v[158:161], v[166:169], v[32:35]
	s_setprio 0
	s_setprio 1
	v_mfma_f32_16x16x32_bf16 v[28:31], v[130:133], v[186:189], v[28:31]
	v_mfma_f32_16x16x32_bf16 v[24:27], v[138:141], v[186:189], v[24:27]
	v_mfma_f32_16x16x32_bf16 v[20:23], v[130:133], v[178:181], v[20:23]
	v_mfma_f32_16x16x32_bf16 v[16:19], v[138:141], v[178:181], v[16:19]
	v_mfma_f32_16x16x32_bf16 v[12:15], v[130:133], v[170:173], v[12:15]
	v_mfma_f32_16x16x32_bf16 v[8:11], v[138:141], v[170:173], v[8:11]
	v_mfma_f32_16x16x32_bf16 v[4:7], v[130:133], v[162:165], v[4:7]
	v_mfma_f32_16x16x32_bf16 v[0:3], v[138:141], v[162:165], v[0:3]
	v_mfma_f32_16x16x32_bf16 v[28:31], v[134:137], v[190:193], v[28:31]
	v_mfma_f32_16x16x32_bf16 v[24:27], v[142:145], v[190:193], v[24:27]
	v_mfma_f32_16x16x32_bf16 v[20:23], v[134:137], v[182:185], v[20:23]
	v_mfma_f32_16x16x32_bf16 v[16:19], v[142:145], v[182:185], v[16:19]
	v_mfma_f32_16x16x32_bf16 v[12:15], v[134:137], v[174:177], v[12:15]
	v_mfma_f32_16x16x32_bf16 v[8:11], v[142:145], v[174:177], v[8:11]
	v_mfma_f32_16x16x32_bf16 v[4:7], v[134:137], v[166:169], v[4:7]
	v_mfma_f32_16x16x32_bf16 v[0:3], v[142:145], v[166:169], v[0:3]
	s_setprio 0
.LBB0_877:
	s_and_b64 s[66:67], s[44:45], s[66:67]
	s_and_b64 s[66:67], s[66:67], exec
	s_cselect_b32 s66, 0, s55
	s_cselect_b32 s67, s4, s54
	s_barrier
	s_add_i32 s89, 0, 0x18000
	v_add_u32_e32 v97, s89, v195
	s_add_i32 vcc_lo, 0, 0x1c000
	ds_read_b128 v[146:149], v97
	ds_read_b128 v[150:153], v97 offset:1024
	ds_read_b128 v[154:157], v97 offset:2048
	ds_read_b128 v[158:161], v97 offset:3072
	v_add_u32_e32 v97, vcc_lo, v195
	ds_read_b128 v[130:133], v97
	ds_read_b128 v[134:137], v97 offset:1024
	ds_read_b128 v[138:141], v97 offset:2048
	ds_read_b128 v[142:145], v97 offset:3072
	s_add_u32 s64, s64, s67
	s_addc_u32 s65, s65, s66
	s_mov_b32 m0, s72
	s_waitcnt lgkmcnt(0)
	ds_read_b128 v[162:165], v251 offset:32768
	ds_read_b128 v[166:169], v251 offset:33792
	ds_read_b128 v[170:173], v251 offset:34816
	ds_read_b128 v[174:177], v251 offset:35840
	ds_read_b128 v[178:181], v251 offset:36864
	ds_read_b128 v[182:185], v251 offset:37888
	ds_read_b128 v[186:189], v251 offset:38912
	ds_read_b128 v[190:193], v251 offset:39936
	global_load_lds_dwordx4 v198, s[64:65]
	s_mov_b32 m0, s73
	s_nop 0
	global_load_lds_dwordx4 v202, s[64:65]
	s_waitcnt vmcnt(8)
	s_waitcnt lgkmcnt(0)
	s_barrier
	s_setprio 1
	s_waitcnt lgkmcnt(0)
	v_mfma_f32_16x16x32_bf16 v[126:129], v[146:149], v[162:165], v[126:129]
	v_mfma_f32_16x16x32_bf16 v[122:125], v[154:157], v[162:165], v[122:125]
	v_mfma_f32_16x16x32_bf16 v[118:121], v[146:149], v[170:173], v[118:121]
	v_mfma_f32_16x16x32_bf16 v[114:117], v[154:157], v[170:173], v[114:117]
	v_mfma_f32_16x16x32_bf16 v[110:113], v[146:149], v[178:181], v[110:113]
	v_mfma_f32_16x16x32_bf16 v[106:109], v[154:157], v[178:181], v[106:109]
	v_mfma_f32_16x16x32_bf16 v[102:105], v[146:149], v[186:189], v[102:105]
	v_mfma_f32_16x16x32_bf16 v[98:101], v[154:157], v[186:189], v[98:101]
	v_mfma_f32_16x16x32_bf16 v[126:129], v[150:153], v[166:169], v[126:129]
	v_mfma_f32_16x16x32_bf16 v[122:125], v[158:161], v[166:169], v[122:125]
	v_mfma_f32_16x16x32_bf16 v[118:121], v[150:153], v[174:177], v[118:121]
	v_mfma_f32_16x16x32_bf16 v[114:117], v[158:161], v[174:177], v[114:117]
	v_mfma_f32_16x16x32_bf16 v[110:113], v[150:153], v[182:185], v[110:113]
	v_mfma_f32_16x16x32_bf16 v[106:109], v[158:161], v[182:185], v[106:109]
	v_mfma_f32_16x16x32_bf16 v[102:105], v[150:153], v[190:193], v[102:105]
	v_mfma_f32_16x16x32_bf16 v[98:101], v[158:161], v[190:193], v[98:101]
	s_setprio 0
	s_setprio 1
	v_mfma_f32_16x16x32_bf16 v[92:95], v[130:133], v[162:165], v[92:95]
	v_mfma_f32_16x16x32_bf16 v[88:91], v[138:141], v[162:165], v[88:91]
	v_mfma_f32_16x16x32_bf16 v[84:87], v[130:133], v[170:173], v[84:87]
	v_mfma_f32_16x16x32_bf16 v[80:83], v[138:141], v[170:173], v[80:83]
	v_mfma_f32_16x16x32_bf16 v[76:79], v[130:133], v[178:181], v[76:79]
	v_mfma_f32_16x16x32_bf16 v[72:75], v[138:141], v[178:181], v[72:75]
	v_mfma_f32_16x16x32_bf16 v[64:67], v[130:133], v[186:189], v[64:67]
	v_mfma_f32_16x16x32_bf16 v[52:55], v[138:141], v[186:189], v[52:55]
	v_mfma_f32_16x16x32_bf16 v[92:95], v[134:137], v[166:169], v[92:95]
	v_mfma_f32_16x16x32_bf16 v[88:91], v[142:145], v[166:169], v[88:91]
	v_mfma_f32_16x16x32_bf16 v[84:87], v[134:137], v[174:177], v[84:87]
	v_mfma_f32_16x16x32_bf16 v[80:83], v[142:145], v[174:177], v[80:83]
	v_mfma_f32_16x16x32_bf16 v[76:79], v[134:137], v[182:185], v[76:79]
	v_mfma_f32_16x16x32_bf16 v[72:75], v[142:145], v[182:185], v[72:75]
	v_mfma_f32_16x16x32_bf16 v[64:67], v[134:137], v[190:193], v[64:67]
	v_mfma_f32_16x16x32_bf16 v[52:55], v[142:145], v[190:193], v[52:55]
	s_setprio 0
	s_barrier
	s_add_i32 s64, s89, s37
	s_add_i32 m0, s64, 0xffffff80
	ds_read_b128 v[186:189], v251 offset:49152
	ds_read_b128 v[190:193], v251 offset:50176
	ds_read_b128 v[178:181], v251 offset:51200
	ds_read_b128 v[182:185], v251 offset:52224
	ds_read_b128 v[170:173], v251 offset:53248
	ds_read_b128 v[174:177], v251 offset:54272
	ds_read_b128 v[162:165], v251 offset:55296
	ds_read_b128 v[166:169], v251 offset:56320
	global_load_lds_dwordx4 v200, s[62:63] offset:128
	s_add_i32 m0, s64, 0x1f80
	s_nop 0
	global_load_lds_dwordx4 v204, s[62:63] offset:128
	s_add_u32 s62, s62, 0x80080
	s_addc_u32 s63, s63, 0
	s_add_i32 s64, vcc_lo, s37
	s_mov_b32 m0, s64
	s_and_b64 vcc, exec, s[38:39]
	global_load_lds_dwordx4 v200, s[62:63]
	s_add_i32 m0, s64, 0x2000
	s_nop 0
	global_load_lds_dwordx4 v204, s[62:63]
	s_add_i32 m0, s76, 0xffffff80
	s_nop 0
	global_load_lds_dwordx4 v198, s[100:101] offset:128
	s_add_i32 m0, s77, 0xffffff80
	s_nop 0
	global_load_lds_dwordx4 v202, s[100:101] offset:128
	s_waitcnt vmcnt(8)
	s_waitcnt lgkmcnt(0)
	s_barrier
	s_cbranch_vccnz .LBB0_874
	s_setprio 1
	s_waitcnt lgkmcnt(0)
	v_mfma_f32_16x16x32_bf16 v[68:71], v[146:149], v[186:189], v[68:71]
	v_mfma_f32_16x16x32_bf16 v[60:63], v[154:157], v[186:189], v[60:63]
	v_mfma_f32_16x16x32_bf16 v[56:59], v[146:149], v[178:181], v[56:59]
	v_mfma_f32_16x16x32_bf16 v[48:51], v[154:157], v[178:181], v[48:51]
	v_mfma_f32_16x16x32_bf16 v[44:47], v[146:149], v[170:173], v[44:47]
	v_mfma_f32_16x16x32_bf16 v[40:43], v[154:157], v[170:173], v[40:43]
	v_mfma_f32_16x16x32_bf16 v[36:39], v[146:149], v[162:165], v[36:39]
	v_mfma_f32_16x16x32_bf16 v[32:35], v[154:157], v[162:165], v[32:35]
	v_mfma_f32_16x16x32_bf16 v[68:71], v[150:153], v[190:193], v[68:71]
	v_mfma_f32_16x16x32_bf16 v[60:63], v[158:161], v[190:193], v[60:63]
	v_mfma_f32_16x16x32_bf16 v[56:59], v[150:153], v[182:185], v[56:59]
	v_mfma_f32_16x16x32_bf16 v[48:51], v[158:161], v[182:185], v[48:51]
	v_mfma_f32_16x16x32_bf16 v[44:47], v[150:153], v[174:177], v[44:47]
	v_mfma_f32_16x16x32_bf16 v[40:43], v[158:161], v[174:177], v[40:43]
	v_mfma_f32_16x16x32_bf16 v[36:39], v[150:153], v[166:169], v[36:39]
	v_mfma_f32_16x16x32_bf16 v[32:35], v[158:161], v[166:169], v[32:35]
	s_setprio 0
	s_setprio 1
	v_mfma_f32_16x16x32_bf16 v[28:31], v[130:133], v[186:189], v[28:31]
	v_mfma_f32_16x16x32_bf16 v[24:27], v[138:141], v[186:189], v[24:27]
	v_mfma_f32_16x16x32_bf16 v[20:23], v[130:133], v[178:181], v[20:23]
	v_mfma_f32_16x16x32_bf16 v[16:19], v[138:141], v[178:181], v[16:19]
	v_mfma_f32_16x16x32_bf16 v[12:15], v[130:133], v[170:173], v[12:15]
	v_mfma_f32_16x16x32_bf16 v[8:11], v[138:141], v[170:173], v[8:11]
	v_mfma_f32_16x16x32_bf16 v[4:7], v[130:133], v[162:165], v[4:7]
	v_mfma_f32_16x16x32_bf16 v[0:3], v[138:141], v[162:165], v[0:3]
	v_mfma_f32_16x16x32_bf16 v[28:31], v[134:137], v[190:193], v[28:31]
	v_mfma_f32_16x16x32_bf16 v[24:27], v[142:145], v[190:193], v[24:27]
	v_mfma_f32_16x16x32_bf16 v[20:23], v[134:137], v[182:185], v[20:23]
	v_mfma_f32_16x16x32_bf16 v[16:19], v[142:145], v[182:185], v[16:19]
	v_mfma_f32_16x16x32_bf16 v[12:15], v[134:137], v[174:177], v[12:15]
	v_mfma_f32_16x16x32_bf16 v[8:11], v[142:145], v[174:177], v[8:11]
	v_mfma_f32_16x16x32_bf16 v[4:7], v[134:137], v[166:169], v[4:7]
	v_mfma_f32_16x16x32_bf16 v[0:3], v[142:145], v[166:169], v[0:3]
	s_setprio 0
	s_branch .LBB0_874

.LBB0_1053:
	s_ashr_i32 s45, s44, 31
	s_lshl_b64 s[26:27], s[44:45], 19
	s_add_u32 s48, s37, s26
	s_addc_u32 s49, s62, s27
	s_and_b64 s[26:27], s[46:47], exec
	s_cselect_b32 s9, s49, s41
	s_cselect_b32 s45, s48, s40
	s_cmp_eq_u32 s75, 2
	s_cselect_b32 s4, 0x80000, 0
	s_cmp_eq_u32 s65, 2
	s_cselect_b64 s[52:53], -1, 0
	s_ashr_i32 s43, s42, 31
	s_lshl_b64 s[26:27], s[42:43], 20
	s_add_u32 s50, s63, s26
	s_addc_u32 s51, s64, s27
	s_and_b64 s[26:27], s[46:47], exec
	s_cselect_b32 s43, s51, s39
	s_cselect_b32 s76, s50, s38
	s_add_u32 s26, s40, 0x80
	s_addc_u32 s27, s41, 0
	v_lshl_add_u64 v[0:1], s[26:27], 0, v[202:203]
	v_lshl_add_u64 v[206:207], v[0:1], 0, s[10:11]
	v_lshl_add_u64 v[0:1], s[26:27], 0, v[204:205]
	v_mov_b32_e32 v97, v96
	v_lshl_add_u64 v[208:209], v[0:1], 0, s[10:11]
	s_add_u32 s77, s38, 0x100
	v_mov_b32_e32 v98, v96
	v_mov_b32_e32 v99, v96
	v_mov_b32_e32 v64, 0
	v_mov_b64_e32 v[0:1], v[96:97]
	v_mov_b64_e32 v[4:5], v[96:97]
	v_mov_b64_e32 v[16:17], v[96:97]
	v_mov_b64_e32 v[20:21], v[96:97]
	v_mov_b64_e32 v[32:33], v[96:97]
	v_mov_b64_e32 v[36:37], v[96:97]
	v_mov_b64_e32 v[48:49], v[96:97]
	v_mov_b64_e32 v[52:53], v[96:97]
	v_mov_b64_e32 v[8:9], v[96:97]
	v_mov_b64_e32 v[12:13], v[96:97]
	v_mov_b64_e32 v[24:25], v[96:97]
	v_mov_b64_e32 v[28:29], v[96:97]
	v_mov_b64_e32 v[40:41], v[96:97]
	v_mov_b64_e32 v[44:45], v[96:97]
	v_mov_b64_e32 v[56:57], v[96:97]
	v_mov_b64_e32 v[60:61], v[96:97]
	s_addc_u32 s26, s39, 0
	s_mov_b32 s27, -2
	s_mov_b64 s[54:55], 0
	v_mov_b64_e32 v[2:3], v[98:99]
	v_mov_b64_e32 v[6:7], v[98:99]
	v_mov_b64_e32 v[18:19], v[98:99]
	v_mov_b64_e32 v[22:23], v[98:99]
	v_mov_b64_e32 v[34:35], v[98:99]
	v_mov_b64_e32 v[38:39], v[98:99]
	v_mov_b64_e32 v[50:51], v[98:99]
	v_mov_b64_e32 v[54:55], v[98:99]
	v_mov_b64_e32 v[10:11], v[98:99]
	v_mov_b64_e32 v[14:15], v[98:99]
	v_mov_b64_e32 v[26:27], v[98:99]
	v_mov_b64_e32 v[30:31], v[98:99]
	v_mov_b64_e32 v[42:43], v[98:99]
	v_mov_b64_e32 v[46:47], v[98:99]
	v_mov_b64_e32 v[58:59], v[98:99]
	v_mov_b64_e32 v[62:63], v[98:99]
	v_mov_b32_e32 v65, v64
	v_mov_b32_e32 v66, v64
	v_mov_b32_e32 v67, v64
	v_mov_b32_e32 v68, v64
	v_mov_b32_e32 v69, v64
	v_mov_b32_e32 v70, v64
	v_mov_b32_e32 v71, v64
	v_mov_b32_e32 v72, v64
	v_mov_b32_e32 v73, v64
	v_mov_b32_e32 v74, v64
	v_mov_b32_e32 v75, v64
	v_mov_b32_e32 v76, v64
	v_mov_b32_e32 v77, v64
	v_mov_b32_e32 v78, v64
	v_mov_b32_e32 v79, v64
	v_mov_b32_e32 v84, v64
	v_mov_b32_e32 v85, v64
	v_mov_b32_e32 v86, v64
	v_mov_b32_e32 v87, v64
	v_mov_b32_e32 v92, v64
	v_mov_b32_e32 v93, v64
	v_mov_b32_e32 v94, v64
	v_mov_b32_e32 v95, v64
	v_mov_b32_e32 v102, v64
	v_mov_b32_e32 v103, v64
	v_mov_b32_e32 v104, v64
	v_mov_b32_e32 v105, v64
	v_mov_b32_e32 v110, v64
	v_mov_b32_e32 v111, v64
	v_mov_b32_e32 v112, v64
	v_mov_b32_e32 v113, v64
	v_mov_b32_e32 v80, v64
	v_mov_b32_e32 v81, v64
	v_mov_b32_e32 v82, v64
	v_mov_b32_e32 v83, v64
	v_mov_b32_e32 v88, v64
	v_mov_b32_e32 v89, v64
	v_mov_b32_e32 v90, v64
	v_mov_b32_e32 v91, v64
	v_mov_b32_e32 v98, v64
	v_mov_b32_e32 v99, v64
	v_mov_b32_e32 v100, v64
	v_mov_b32_e32 v101, v64
	v_mov_b32_e32 v106, v64
	v_mov_b32_e32 v107, v64
	v_mov_b32_e32 v108, v64
	v_mov_b32_e32 v109, v64
	v_mov_b32_e32 v114, v64
	v_mov_b32_e32 v115, v64
	v_mov_b32_e32 v116, v64
	v_mov_b32_e32 v117, v64
	v_mov_b32_e32 v118, v64
	v_mov_b32_e32 v119, v64
	v_mov_b32_e32 v120, v64
	v_mov_b32_e32 v121, v64
	v_mov_b32_e32 v122, v64
	v_mov_b32_e32 v123, v64
	v_mov_b32_e32 v124, v64
	v_mov_b32_e32 v125, v64
	v_mov_b32_e32 v126, v64
	v_mov_b32_e32 v127, v64
	v_mov_b32_e32 v128, v64
	v_mov_b32_e32 v129, v64
	v_add_u32_e32 v224, 0x10000, v218
	v_add_u32_e32 v225, 0x14000, v218
	v_add_u32_e32 v226, 0x18000, v218
	v_add_u32_e32 v227, 0x1c000, v218
	s_branch .LBB0_1055

.LBB0_1055:
	s_add_u32 s38, s40, s54
	s_addc_u32 s39, s41, s55
	s_add_u32 s56, s38, 0x100
	s_addc_u32 s57, s39, 0
	s_add_i32 s78, 0, 0x10000
	s_add_u32 s79, s77, s54
	s_addc_u32 s80, s26, s55
	s_cmpk_eq_i32 s54, 0xf00
	s_cselect_b64 s[60:61], -1, 0
	s_and_b64 s[38:39], s[60:61], exec
	s_cselect_b32 s59, s9, s57
	s_cselect_b32 s58, s45, s56
	s_cselect_b32 s57, s43, s80
	s_cselect_b32 s56, s76, s79
	s_add_i32 s79, 0, 0x14000
	ds_read_b128 v[146:149], v224
	ds_read_b128 v[150:153], v224 offset:1024
	ds_read_b128 v[154:157], v224 offset:2048
	ds_read_b128 v[158:161], v224 offset:3072
	ds_read_b128 v[130:133], v225
	ds_read_b128 v[134:137], v225 offset:1024
	ds_read_b128 v[138:141], v225 offset:2048
	ds_read_b128 v[142:145], v225 offset:3072
	v_lshl_add_u64 v[210:211], v[208:209], 0, s[54:55]
	s_add_i32 m0, s13, 0xc000
	s_waitcnt lgkmcnt(0)
	ds_read_b128 v[162:165], v220
	ds_read_b128 v[166:169], v220 offset:1024
	ds_read_b128 v[170:173], v220 offset:2048
	ds_read_b128 v[174:177], v220 offset:3072
	ds_read_b128 v[178:181], v220 offset:4096
	ds_read_b128 v[182:185], v220 offset:5120
	ds_read_b128 v[186:189], v220 offset:6144
	ds_read_b128 v[190:193], v220 offset:7168
	global_load_lds_dwordx4 v[210:211], off
	v_lshl_add_u64 v[210:211], v[206:207], 0, s[54:55]
	s_add_i32 m0, s13, 0xe000
	s_nop 0
	global_load_lds_dwordx4 v[210:211], off
	s_waitcnt vmcnt(8)
	s_waitcnt lgkmcnt(0)
	s_barrier
	s_setprio 1
	s_waitcnt lgkmcnt(0)
	v_mfma_f32_16x16x32_bf16 v[126:129], v[146:149], v[162:165], v[126:129]
	v_mfma_f32_16x16x32_bf16 v[122:125], v[154:157], v[162:165], v[122:125]
	v_mfma_f32_16x16x32_bf16 v[118:121], v[146:149], v[170:173], v[118:121]
	v_mfma_f32_16x16x32_bf16 v[114:117], v[154:157], v[170:173], v[114:117]
	v_mfma_f32_16x16x32_bf16 v[106:109], v[146:149], v[178:181], v[106:109]
	v_mfma_f32_16x16x32_bf16 v[98:101], v[154:157], v[178:181], v[98:101]
	v_mfma_f32_16x16x32_bf16 v[88:91], v[146:149], v[186:189], v[88:91]
	v_mfma_f32_16x16x32_bf16 v[80:83], v[154:157], v[186:189], v[80:83]
	v_mfma_f32_16x16x32_bf16 v[126:129], v[150:153], v[166:169], v[126:129]
	v_mfma_f32_16x16x32_bf16 v[122:125], v[158:161], v[166:169], v[122:125]
	v_mfma_f32_16x16x32_bf16 v[118:121], v[150:153], v[174:177], v[118:121]
	v_mfma_f32_16x16x32_bf16 v[114:117], v[158:161], v[174:177], v[114:117]
	v_mfma_f32_16x16x32_bf16 v[106:109], v[150:153], v[182:185], v[106:109]
	v_mfma_f32_16x16x32_bf16 v[98:101], v[158:161], v[182:185], v[98:101]
	v_mfma_f32_16x16x32_bf16 v[88:91], v[150:153], v[190:193], v[88:91]
	v_mfma_f32_16x16x32_bf16 v[80:83], v[158:161], v[190:193], v[80:83]
	s_setprio 0
	s_setprio 1
	v_mfma_f32_16x16x32_bf16 v[110:113], v[130:133], v[162:165], v[110:113]
	v_mfma_f32_16x16x32_bf16 v[102:105], v[138:141], v[162:165], v[102:105]
	v_mfma_f32_16x16x32_bf16 v[92:95], v[130:133], v[170:173], v[92:95]
	v_mfma_f32_16x16x32_bf16 v[84:87], v[138:141], v[170:173], v[84:87]
	v_mfma_f32_16x16x32_bf16 v[76:79], v[130:133], v[178:181], v[76:79]
	v_mfma_f32_16x16x32_bf16 v[72:75], v[138:141], v[178:181], v[72:75]
	v_mfma_f32_16x16x32_bf16 v[68:71], v[130:133], v[186:189], v[68:71]
	v_mfma_f32_16x16x32_bf16 v[64:67], v[138:141], v[186:189], v[64:67]
	v_mfma_f32_16x16x32_bf16 v[110:113], v[134:137], v[166:169], v[110:113]
	v_mfma_f32_16x16x32_bf16 v[102:105], v[142:145], v[166:169], v[102:105]
	v_mfma_f32_16x16x32_bf16 v[92:95], v[134:137], v[174:177], v[92:95]
	v_mfma_f32_16x16x32_bf16 v[84:87], v[142:145], v[174:177], v[84:87]
	v_mfma_f32_16x16x32_bf16 v[76:79], v[134:137], v[182:185], v[76:79]
	v_mfma_f32_16x16x32_bf16 v[72:75], v[142:145], v[182:185], v[72:75]
	v_mfma_f32_16x16x32_bf16 v[68:71], v[134:137], v[190:193], v[68:71]
	v_mfma_f32_16x16x32_bf16 v[64:67], v[142:145], v[190:193], v[64:67]
	s_setprio 0
	s_barrier
	s_add_i32 s38, s78, s66
	s_mov_b32 m0, s38
	ds_read_b128 v[186:189], v220 offset:16384
	ds_read_b128 v[190:193], v220 offset:17408
	ds_read_b128 v[178:181], v220 offset:18432
	ds_read_b128 v[182:185], v220 offset:19456
	ds_read_b128 v[170:173], v220 offset:20480
	ds_read_b128 v[174:177], v220 offset:21504
	ds_read_b128 v[162:165], v220 offset:22528
	ds_read_b128 v[166:169], v220 offset:23552
	global_load_lds_dwordx4 v198, s[56:57]
	s_add_i32 m0, s38, 0x2000
	s_add_u32 s38, s56, 0x80000
	s_addc_u32 s39, s57, 0
	s_add_i32 s78, s79, s66
	global_load_lds_dwordx4 v200, s[56:57]
	s_mov_b32 m0, s78
	s_mov_b64 s[100:101], s[58:59]
	global_load_lds_dwordx4 v198, s[38:39]
	s_add_i32 m0, s78, 0x2000
	s_nop 0
	global_load_lds_dwordx4 v200, s[38:39]
	s_mov_b32 m0, s13
	s_andn2_b64 s[38:39], exec, s[52:53]
	global_load_lds_dwordx4 v198, s[100:101]
	s_mov_b32 m0, s67
	s_andn2_b64 vcc, exec, s[52:53]
	global_load_lds_dwordx4 v200, s[100:101]
	s_waitcnt vmcnt(8)
	s_waitcnt lgkmcnt(0)
	s_barrier
	s_cbranch_vccnz .LBB0_1057
	s_setprio 1
	s_waitcnt lgkmcnt(0)
	v_mfma_f32_16x16x32_bf16 v[60:63], v[146:149], v[186:189], v[60:63]
	v_mfma_f32_16x16x32_bf16 v[56:59], v[154:157], v[186:189], v[56:59]
	v_mfma_f32_16x16x32_bf16 v[44:47], v[146:149], v[178:181], v[44:47]
	v_mfma_f32_16x16x32_bf16 v[40:43], v[154:157], v[178:181], v[40:43]
	v_mfma_f32_16x16x32_bf16 v[28:31], v[146:149], v[170:173], v[28:31]
	v_mfma_f32_16x16x32_bf16 v[24:27], v[154:157], v[170:173], v[24:27]
	v_mfma_f32_16x16x32_bf16 v[12:15], v[146:149], v[162:165], v[12:15]
	v_mfma_f32_16x16x32_bf16 v[8:11], v[154:157], v[162:165], v[8:11]
	v_mfma_f32_16x16x32_bf16 v[60:63], v[150:153], v[190:193], v[60:63]
	v_mfma_f32_16x16x32_bf16 v[56:59], v[158:161], v[190:193], v[56:59]
	v_mfma_f32_16x16x32_bf16 v[44:47], v[150:153], v[182:185], v[44:47]
	v_mfma_f32_16x16x32_bf16 v[40:43], v[158:161], v[182:185], v[40:43]
	v_mfma_f32_16x16x32_bf16 v[28:31], v[150:153], v[174:177], v[28:31]
	v_mfma_f32_16x16x32_bf16 v[24:27], v[158:161], v[174:177], v[24:27]
	v_mfma_f32_16x16x32_bf16 v[12:15], v[150:153], v[166:169], v[12:15]
	v_mfma_f32_16x16x32_bf16 v[8:11], v[158:161], v[166:169], v[8:11]
	s_setprio 0
	s_setprio 1
	v_mfma_f32_16x16x32_bf16 v[52:55], v[130:133], v[186:189], v[52:55]
	v_mfma_f32_16x16x32_bf16 v[48:51], v[138:141], v[186:189], v[48:51]
	v_mfma_f32_16x16x32_bf16 v[36:39], v[130:133], v[178:181], v[36:39]
	v_mfma_f32_16x16x32_bf16 v[32:35], v[138:141], v[178:181], v[32:35]
	v_mfma_f32_16x16x32_bf16 v[20:23], v[130:133], v[170:173], v[20:23]
	v_mfma_f32_16x16x32_bf16 v[16:19], v[138:141], v[170:173], v[16:19]
	v_mfma_f32_16x16x32_bf16 v[4:7], v[130:133], v[162:165], v[4:7]
	v_mfma_f32_16x16x32_bf16 v[0:3], v[138:141], v[162:165], v[0:3]
	v_mfma_f32_16x16x32_bf16 v[52:55], v[134:137], v[190:193], v[52:55]
	v_mfma_f32_16x16x32_bf16 v[48:51], v[142:145], v[190:193], v[48:51]
	v_mfma_f32_16x16x32_bf16 v[36:39], v[134:137], v[182:185], v[36:39]
	v_mfma_f32_16x16x32_bf16 v[32:35], v[142:145], v[182:185], v[32:35]
	v_mfma_f32_16x16x32_bf16 v[20:23], v[134:137], v[174:177], v[20:23]
	v_mfma_f32_16x16x32_bf16 v[16:19], v[142:145], v[174:177], v[16:19]
	v_mfma_f32_16x16x32_bf16 v[4:7], v[134:137], v[166:169], v[4:7]
	v_mfma_f32_16x16x32_bf16 v[0:3], v[142:145], v[166:169], v[0:3]
	s_setprio 0
.LBB0_1057:
	s_and_b64 s[60:61], s[46:47], s[60:61]
	s_and_b64 s[60:61], s[60:61], exec
	s_cselect_b32 s60, 0, s11
	s_cselect_b32 s61, s4, s10
	s_barrier
	s_add_i32 s78, 0, 0x18000
	s_add_i32 s79, 0, 0x1c000
	ds_read_b128 v[146:149], v226
	ds_read_b128 v[150:153], v226 offset:1024
	ds_read_b128 v[154:157], v226 offset:2048
	ds_read_b128 v[158:161], v226 offset:3072
	ds_read_b128 v[130:133], v227
	ds_read_b128 v[134:137], v227 offset:1024
	ds_read_b128 v[138:141], v227 offset:2048
	ds_read_b128 v[142:145], v227 offset:3072
	s_add_u32 s58, s58, s61
	s_addc_u32 s59, s59, s60
	s_mov_b32 m0, s68
	s_waitcnt lgkmcnt(0)
	ds_read_b128 v[162:165], v220 offset:32768
	ds_read_b128 v[166:169], v220 offset:33792
	ds_read_b128 v[170:173], v220 offset:34816
	ds_read_b128 v[174:177], v220 offset:35840
	ds_read_b128 v[178:181], v220 offset:36864
	ds_read_b128 v[182:185], v220 offset:37888
	ds_read_b128 v[186:189], v220 offset:38912
	ds_read_b128 v[190:193], v220 offset:39936
	global_load_lds_dwordx4 v198, s[58:59]
	s_mov_b32 m0, s69
	s_nop 0
	global_load_lds_dwordx4 v200, s[58:59]
	s_waitcnt vmcnt(8)
	s_waitcnt lgkmcnt(0)
	s_barrier
	s_setprio 1
	s_waitcnt lgkmcnt(0)
	v_mfma_f32_16x16x32_bf16 v[126:129], v[146:149], v[162:165], v[126:129]
	v_mfma_f32_16x16x32_bf16 v[122:125], v[154:157], v[162:165], v[122:125]
	v_mfma_f32_16x16x32_bf16 v[118:121], v[146:149], v[170:173], v[118:121]
	v_mfma_f32_16x16x32_bf16 v[114:117], v[154:157], v[170:173], v[114:117]
	v_mfma_f32_16x16x32_bf16 v[106:109], v[146:149], v[178:181], v[106:109]
	v_mfma_f32_16x16x32_bf16 v[98:101], v[154:157], v[178:181], v[98:101]
	v_mfma_f32_16x16x32_bf16 v[88:91], v[146:149], v[186:189], v[88:91]
	v_mfma_f32_16x16x32_bf16 v[80:83], v[154:157], v[186:189], v[80:83]
	v_mfma_f32_16x16x32_bf16 v[126:129], v[150:153], v[166:169], v[126:129]
	v_mfma_f32_16x16x32_bf16 v[122:125], v[158:161], v[166:169], v[122:125]
	v_mfma_f32_16x16x32_bf16 v[118:121], v[150:153], v[174:177], v[118:121]
	v_mfma_f32_16x16x32_bf16 v[114:117], v[158:161], v[174:177], v[114:117]
	v_mfma_f32_16x16x32_bf16 v[106:109], v[150:153], v[182:185], v[106:109]
	v_mfma_f32_16x16x32_bf16 v[98:101], v[158:161], v[182:185], v[98:101]
	v_mfma_f32_16x16x32_bf16 v[88:91], v[150:153], v[190:193], v[88:91]
	v_mfma_f32_16x16x32_bf16 v[80:83], v[158:161], v[190:193], v[80:83]
	s_setprio 0
	s_setprio 1
	v_mfma_f32_16x16x32_bf16 v[110:113], v[130:133], v[162:165], v[110:113]
	v_mfma_f32_16x16x32_bf16 v[102:105], v[138:141], v[162:165], v[102:105]
	v_mfma_f32_16x16x32_bf16 v[92:95], v[130:133], v[170:173], v[92:95]
	v_mfma_f32_16x16x32_bf16 v[84:87], v[138:141], v[170:173], v[84:87]
	v_mfma_f32_16x16x32_bf16 v[76:79], v[130:133], v[178:181], v[76:79]
	v_mfma_f32_16x16x32_bf16 v[72:75], v[138:141], v[178:181], v[72:75]
	v_mfma_f32_16x16x32_bf16 v[68:71], v[130:133], v[186:189], v[68:71]
	v_mfma_f32_16x16x32_bf16 v[64:67], v[138:141], v[186:189], v[64:67]
	v_mfma_f32_16x16x32_bf16 v[110:113], v[134:137], v[166:169], v[110:113]
	v_mfma_f32_16x16x32_bf16 v[102:105], v[142:145], v[166:169], v[102:105]
	v_mfma_f32_16x16x32_bf16 v[92:95], v[134:137], v[174:177], v[92:95]
	v_mfma_f32_16x16x32_bf16 v[84:87], v[142:145], v[174:177], v[84:87]
	v_mfma_f32_16x16x32_bf16 v[76:79], v[134:137], v[182:185], v[76:79]
	v_mfma_f32_16x16x32_bf16 v[72:75], v[142:145], v[182:185], v[72:75]
	v_mfma_f32_16x16x32_bf16 v[68:71], v[134:137], v[190:193], v[68:71]
	v_mfma_f32_16x16x32_bf16 v[64:67], v[142:145], v[190:193], v[64:67]
	s_setprio 0
	s_barrier
	s_add_i32 s58, s78, s66
	s_add_i32 m0, s58, 0xffffff80
	ds_read_b128 v[186:189], v220 offset:49152
	ds_read_b128 v[190:193], v220 offset:50176
	ds_read_b128 v[178:181], v220 offset:51200
	ds_read_b128 v[182:185], v220 offset:52224
	ds_read_b128 v[170:173], v220 offset:53248
	ds_read_b128 v[174:177], v220 offset:54272
	ds_read_b128 v[162:165], v220 offset:55296
	ds_read_b128 v[166:169], v220 offset:56320
	global_load_lds_dwordx4 v198, s[56:57] offset:128
	s_add_i32 m0, s58, 0x1f80
	s_nop 0
	global_load_lds_dwordx4 v200, s[56:57] offset:128
	s_add_u32 s56, s56, 0x80080
	s_addc_u32 s57, s57, 0
	s_add_i32 s58, s79, s66
	s_mov_b32 m0, s58
	s_and_b64 vcc, exec, s[38:39]
	global_load_lds_dwordx4 v198, s[56:57]
	s_add_i32 m0, s58, 0x2000
	s_mov_b64 s[80:81], 0x7ff
	global_load_lds_dwordx4 v200, s[56:57]
	s_add_i32 m0, s70, 0xffffff80
	s_nop 0
	global_load_lds_dwordx4 v198, s[100:101] offset:128
	s_add_i32 m0, s71, 0xffffff80
	s_nop 0
	global_load_lds_dwordx4 v200, s[100:101] offset:128
	s_waitcnt vmcnt(8)
	s_waitcnt lgkmcnt(0)
	s_barrier
	s_cbranch_vccnz .LBB0_1054
	s_setprio 1
	s_waitcnt lgkmcnt(0)
	v_mfma_f32_16x16x32_bf16 v[60:63], v[146:149], v[186:189], v[60:63]
	v_mfma_f32_16x16x32_bf16 v[56:59], v[154:157], v[186:189], v[56:59]
	v_mfma_f32_16x16x32_bf16 v[44:47], v[146:149], v[178:181], v[44:47]
	v_mfma_f32_16x16x32_bf16 v[40:43], v[154:157], v[178:181], v[40:43]
	v_mfma_f32_16x16x32_bf16 v[28:31], v[146:149], v[170:173], v[28:31]
	v_mfma_f32_16x16x32_bf16 v[24:27], v[154:157], v[170:173], v[24:27]
	v_mfma_f32_16x16x32_bf16 v[12:15], v[146:149], v[162:165], v[12:15]
	v_mfma_f32_16x16x32_bf16 v[8:11], v[154:157], v[162:165], v[8:11]
	v_mfma_f32_16x16x32_bf16 v[60:63], v[150:153], v[190:193], v[60:63]
	v_mfma_f32_16x16x32_bf16 v[56:59], v[158:161], v[190:193], v[56:59]
	v_mfma_f32_16x16x32_bf16 v[44:47], v[150:153], v[182:185], v[44:47]
	v_mfma_f32_16x16x32_bf16 v[40:43], v[158:161], v[182:185], v[40:43]
	v_mfma_f32_16x16x32_bf16 v[28:31], v[150:153], v[174:177], v[28:31]
	v_mfma_f32_16x16x32_bf16 v[24:27], v[158:161], v[174:177], v[24:27]
	v_mfma_f32_16x16x32_bf16 v[12:15], v[150:153], v[166:169], v[12:15]
	v_mfma_f32_16x16x32_bf16 v[8:11], v[158:161], v[166:169], v[8:11]
	s_setprio 0
	s_setprio 1
	v_mfma_f32_16x16x32_bf16 v[52:55], v[130:133], v[186:189], v[52:55]
	v_mfma_f32_16x16x32_bf16 v[48:51], v[138:141], v[186:189], v[48:51]
	v_mfma_f32_16x16x32_bf16 v[36:39], v[130:133], v[178:181], v[36:39]
	v_mfma_f32_16x16x32_bf16 v[32:35], v[138:141], v[178:181], v[32:35]
	v_mfma_f32_16x16x32_bf16 v[20:23], v[130:133], v[170:173], v[20:23]
	v_mfma_f32_16x16x32_bf16 v[16:19], v[138:141], v[170:173], v[16:19]
	v_mfma_f32_16x16x32_bf16 v[4:7], v[130:133], v[162:165], v[4:7]
	v_mfma_f32_16x16x32_bf16 v[0:3], v[138:141], v[162:165], v[0:3]
	v_mfma_f32_16x16x32_bf16 v[52:55], v[134:137], v[190:193], v[52:55]
	v_mfma_f32_16x16x32_bf16 v[48:51], v[142:145], v[190:193], v[48:51]
	v_mfma_f32_16x16x32_bf16 v[36:39], v[134:137], v[182:185], v[36:39]
	v_mfma_f32_16x16x32_bf16 v[32:35], v[142:145], v[182:185], v[32:35]
	v_mfma_f32_16x16x32_bf16 v[20:23], v[134:137], v[174:177], v[20:23]
	v_mfma_f32_16x16x32_bf16 v[16:19], v[142:145], v[174:177], v[16:19]
	v_mfma_f32_16x16x32_bf16 v[4:7], v[134:137], v[166:169], v[4:7]
	v_mfma_f32_16x16x32_bf16 v[0:3], v[142:145], v[166:169], v[0:3]
	s_setprio 0
	s_branch .LBB0_1054
